# v47 + saddr: in-loop LDS-DMA of 5 GEMM K-loops converted to SGPR-base + 32-bit VGPR-offset form; removes 16 loader v_lshl_add_u64 per iteration (bases derived with SALU into s98-s101)
# speedup vs baseline: 1.0045x; 1.0045x over previous
; #define PG8_STAGE(bufoff, gbase, voff) do { _Pragma("unroll") for (int _i = 0; _i < 2; ++_i) \
;         __builtin_amdgcn_global_load_lds((const unsigned*)((const char*)(gbase) + (voff)[_i]), (LAS unsigned*)(lds + (bufoff) + ldsw + _i * 8192), 16, 0, 0); } while (0)
; #define PG8_LDA(dst, b, h) do { _Pragma("unroll") for (int m = 0; m < 4; ++m) _Pragma("unroll") for (int k = 0; k < 2; ++k) dst[m][k] = *(const LAS bf16x8*)(lds + PG8_SA(b, h) + aoffk[k] + m * 2048); } while (0)
; #define PG8_LDB(dst, b, h) do { _Pragma("unroll") for (int n = 0; n < 2; ++n) _Pragma("unroll") for (int k = 0; k < 2; ++k) dst[n][k] = *(const LAS bf16x8*)(lds + PG8_SB(b, h) + boffk[k] + n * 2048); } while (0)
; #define PG8_WAIT_V(n) asm volatile("s_waitcnt vmcnt(" #n ")" ::: "memory")
; #define PG8_WAIT_L(n) asm volatile("s_waitcnt lgkmcnt(" #n ")" ::: "memory")
; #define PG8_BAR __builtin_amdgcn_s_barrier()
; #define PG8_SCHED __builtin_amdgcn_sched_barrier(0)
; template <class Epi, class Sched, class GemmT>
; __device__ __forceinline__ void gemm_phase(LAS unsigned char* lds, const GemmT& g, const Sched& S, const Epi& E, const int wid) {
;     ...
;                 PG8_LDB(B0, 0, 0); PG8_LDB(B1, 0, 1); PG8_SCHED; PG8_LDA(At, 0, 0); PG8_STAGE(PG8_SA(1, 1), a1 + hstepA, voffA);
;                 PG8_WAIT_V(8); PG8_WAIT_L(0); PG8_BAR; PG8_MMA(0, 0, At, B0); PG8_MMA(0, 1, At, B1); PG8_BAR; PG8_SCHED;
;                 PG8_LDA(At, 0, 1); PG8_STAGE(PG8_SB(0, 0), b2, vB2); PG8_STAGE(PG8_SB(0, 1), b2 + hB2, vB2); PG8_STAGE(PG8_SA(0, 0), a2, vA2);
;                 PG8_WAIT_V(8); PG8_WAIT_L(0); PG8_BAR; PG8_MMA(1, 0, At, B0); PG8_MMA(1, 1, At, B1); PG8_BAR; PG8_SCHED;
.LBB0_361:
	ds_read_b128 v[24:27], v186
	ds_read_b128 v[28:31], v187
	ds_read_b128 v[16:19], v188
	ds_read_b128 v[20:23], v189
	ds_read_b128 v[8:11], v190
	ds_read_b128 v[12:15], v191
	ds_read_b128 v[0:3], v192
	ds_read_b128 v[4:7], v193
	s_add_u32 s41, s56, 0xfff80080
	s_addc_u32 s48, s57, -1
	s_cmp_eq_u32 s40, 28
	s_cselect_b32 s83, s43, s48
	s_cselect_b32 s82, s42, s41
	s_cselect_b32 s59, s37, s39
	s_cselect_b32 s58, s36, s38
	s_add_i32 m0, s12, 0xc000
	ds_read_b128 v[174:177], v194
	ds_read_b128 v[204:207], v194 offset:2048
	ds_read_b128 v[178:181], v195
	ds_read_b128 v[208:211], v195 offset:2048
	ds_read_b128 v[212:215], v194 offset:4096
	ds_read_b128 v[220:223], v194 offset:6144
	ds_read_b128 v[216:219], v195 offset:4096
	ds_read_b128 v[224:227], v195 offset:6144
	global_load_lds_dwordx4 v160, s[56:57]
	s_add_i32 m0, s12, 0xe000
	s_nop 0
	global_load_lds_dwordx4 v164, s[56:57]
	s_waitcnt vmcnt(8)
	s_waitcnt lgkmcnt(0)
	s_waitcnt lgkmcnt(0)
	v_mfma_scale_f32_16x16x128_f8f6f4 v[156:159], v[24:31], v[174:181], v[156:159], v196, v196 op_sel_hi:[0,0,0]
	v_mfma_scale_f32_16x16x128_f8f6f4 v[152:155], v[16:23], v[174:181], v[152:155], v196, v196 op_sel_hi:[0,0,0]
	s_barrier
	s_setprio 3
	v_mfma_scale_f32_16x16x128_f8f6f4 v[136:139], v[16:23], v[204:211], v[136:139], v196, v196 op_sel_hi:[0,0,0]
	v_mfma_scale_f32_16x16x128_f8f6f4 v[140:143], v[24:31], v[204:211], v[140:143], v196, v196 op_sel_hi:[0,0,0]
	v_mfma_scale_f32_16x16x128_f8f6f4 v[124:127], v[24:31], v[212:219], v[124:127], v196, v196 op_sel_hi:[0,0,0]
	v_mfma_scale_f32_16x16x128_f8f6f4 v[120:123], v[16:23], v[212:219], v[120:123], v196, v196 op_sel_hi:[0,0,0]
	v_mfma_scale_f32_16x16x128_f8f6f4 v[104:107], v[16:23], v[220:227], v[104:107], v196, v196 op_sel_hi:[0,0,0]
	v_mfma_scale_f32_16x16x128_f8f6f4 v[108:111], v[24:31], v[220:227], v[108:111], v196, v196 op_sel_hi:[0,0,0]
	s_setprio 0
	s_setprio 3
	v_mfma_scale_f32_16x16x128_f8f6f4 v[148:151], v[8:15], v[174:181], v[148:151], v196, v196 op_sel_hi:[0,0,0]
	v_mfma_scale_f32_16x16x128_f8f6f4 v[144:147], v[0:7], v[174:181], v[144:147], v196, v196 op_sel_hi:[0,0,0]
	v_mfma_scale_f32_16x16x128_f8f6f4 v[128:131], v[0:7], v[204:211], v[128:131], v196, v196 op_sel_hi:[0,0,0]
	v_mfma_scale_f32_16x16x128_f8f6f4 v[132:135], v[8:15], v[204:211], v[132:135], v196, v196 op_sel_hi:[0,0,0]
	v_mfma_scale_f32_16x16x128_f8f6f4 v[116:119], v[8:15], v[212:219], v[116:119], v196, v196 op_sel_hi:[0,0,0]
	v_mfma_scale_f32_16x16x128_f8f6f4 v[112:115], v[0:7], v[212:219], v[112:115], v196, v196 op_sel_hi:[0,0,0]
	v_mfma_scale_f32_16x16x128_f8f6f4 v[96:99], v[0:7], v[220:227], v[96:99], v196, v196 op_sel_hi:[0,0,0]
	v_mfma_scale_f32_16x16x128_f8f6f4 v[100:103], v[8:15], v[220:227], v[100:103], v196, v196 op_sel_hi:[0,0,0]
	s_setprio 0
	s_barrier
	s_add_i32 s41, s64, s68
	s_mov_b32 m0, s41
	ds_read_b128 v[204:207], v194 offset:16384
	ds_read_b128 v[212:215], v194 offset:18432
	ds_read_b128 v[208:211], v195 offset:16384
	ds_read_b128 v[216:219], v195 offset:18432
	ds_read_b128 v[220:223], v194 offset:20480
	ds_read_b128 v[230:233], v194 offset:22528
	ds_read_b128 v[224:227], v195 offset:20480
	ds_read_b128 v[234:237], v195 offset:22528
	global_load_lds_dwordx4 v162, s[58:59]
	s_add_i32 m0, s41, 0x2000
	s_add_u32 s50, s58, 0x80000
	s_addc_u32 s51, s59, 0
	s_add_i32 s41, s65, s68
	global_load_lds_dwordx4 v166, s[58:59]
	s_mov_b32 m0, s41
	s_nop 0
	global_load_lds_dwordx4 v162, s[50:51]
	s_add_i32 m0, s41, 0x2000
	s_nop 0
	global_load_lds_dwordx4 v166, s[50:51]
	s_mov_b32 m0, s12
	s_nop 0
	global_load_lds_dwordx4 v160, s[82:83]
	s_mov_b32 m0, s13
	s_nop 0
	global_load_lds_dwordx4 v164, s[82:83]
	s_waitcnt vmcnt(8)
	s_waitcnt lgkmcnt(0)
	s_waitcnt lgkmcnt(0)
	v_mfma_scale_f32_16x16x128_f8f6f4 v[84:87], v[24:31], v[204:211], v[84:87], v196, v196 op_sel_hi:[0,0,0]
	v_mfma_scale_f32_16x16x128_f8f6f4 v[80:83], v[16:23], v[204:211], v[80:83], v196, v196 op_sel_hi:[0,0,0]
	s_barrier
	s_setprio 3
	v_mfma_scale_f32_16x16x128_f8f6f4 v[64:67], v[16:23], v[212:219], v[64:67], v196, v196 op_sel_hi:[0,0,0]
	v_mfma_scale_f32_16x16x128_f8f6f4 v[68:71], v[24:31], v[212:219], v[68:71], v196, v196 op_sel_hi:[0,0,0]
	v_mfma_scale_f32_16x16x128_f8f6f4 v[52:55], v[24:31], v[220:227], v[52:55], v196, v196 op_sel_hi:[0,0,0]
	v_mfma_scale_f32_16x16x128_f8f6f4 v[48:51], v[16:23], v[220:227], v[48:51], v196, v196 op_sel_hi:[0,0,0]
	v_mfma_scale_f32_16x16x128_f8f6f4 v[32:35], v[16:23], v[230:237], v[32:35], v196, v196 op_sel_hi:[0,0,0]
	v_mfma_scale_f32_16x16x128_f8f6f4 v[36:39], v[24:31], v[230:237], v[36:39], v196, v196 op_sel_hi:[0,0,0]
	s_setprio 0
	s_setprio 3
	v_mfma_scale_f32_16x16x128_f8f6f4 v[92:95], v[8:15], v[204:211], v[92:95], v196, v196 op_sel_hi:[0,0,0]
	v_mfma_scale_f32_16x16x128_f8f6f4 v[88:91], v[0:7], v[204:211], v[88:91], v196, v196 op_sel_hi:[0,0,0]
	v_mfma_scale_f32_16x16x128_f8f6f4 v[72:75], v[0:7], v[212:219], v[72:75], v196, v196 op_sel_hi:[0,0,0]
	v_mfma_scale_f32_16x16x128_f8f6f4 v[76:79], v[8:15], v[212:219], v[76:79], v196, v196 op_sel_hi:[0,0,0]
	v_mfma_scale_f32_16x16x128_f8f6f4 v[60:63], v[8:15], v[220:227], v[60:63], v196, v196 op_sel_hi:[0,0,0]
	v_mfma_scale_f32_16x16x128_f8f6f4 v[56:59], v[0:7], v[220:227], v[56:59], v196, v196 op_sel_hi:[0,0,0]
	v_mfma_scale_f32_16x16x128_f8f6f4 v[40:43], v[0:7], v[230:237], v[40:43], v196, v196 op_sel_hi:[0,0,0]
	v_mfma_scale_f32_16x16x128_f8f6f4 v[44:47], v[8:15], v[230:237], v[44:47], v196, v196 op_sel_hi:[0,0,0]
	s_setprio 0
	s_barrier
; #define PG8_STAGE(bufoff, gbase, voff) do { _Pragma("unroll") for (int _i = 0; _i < 2; ++_i) \
;         __builtin_amdgcn_global_load_lds((const unsigned*)((const char*)(gbase) + (voff)[_i]), (LAS unsigned*)(lds + (bufoff) + ldsw + _i * 8192), 16, 0, 0); } while (0)
; #define PG8_LDA(dst, b, h) do { _Pragma("unroll") for (int m = 0; m < 4; ++m) _Pragma("unroll") for (int k = 0; k < 2; ++k) dst[m][k] = *(const LAS bf16x8*)(lds + PG8_SA(b, h) + aoffk[k] + m * 2048); } while (0)
; #define PG8_LDB(dst, b, h) do { _Pragma("unroll") for (int n = 0; n < 2; ++n) _Pragma("unroll") for (int k = 0; k < 2; ++k) dst[n][k] = *(const LAS bf16x8*)(lds + PG8_SB(b, h) + boffk[k] + n * 2048); } while (0)
; #define PG8_WAIT_V(n) asm volatile("s_waitcnt vmcnt(" #n ")" ::: "memory")
; #define PG8_WAIT_L(n) asm volatile("s_waitcnt lgkmcnt(" #n ")" ::: "memory")
; #define PG8_BAR __builtin_amdgcn_s_barrier()
; #define PG8_SCHED __builtin_amdgcn_sched_barrier(0)
; template <class Epi, class Sched, class GemmT>
; __device__ __forceinline__ void gemm_phase(LAS unsigned char* lds, const GemmT& g, const Sched& S, const Epi& E, const int wid) {
;     ...
;                 PG8_LDB(B0, 1, 0); PG8_LDB(B1, 1, 1); PG8_SCHED; PG8_LDA(At, 1, 0); PG8_STAGE(PG8_SA(0, 1), a2 + hA2, vA2);
;                 PG8_WAIT_V(8); PG8_WAIT_L(0); PG8_BAR; PG8_MMA(0, 0, At, B0); PG8_MMA(0, 1, At, B1); PG8_BAR; PG8_SCHED;
;                 PG8_LDA(At, 1, 1); PG8_STAGE(PG8_SB(1, 0), b3, vB2); PG8_STAGE(PG8_SB(1, 1), b3 + hB2, vB2); PG8_STAGE(PG8_SA(1, 0), a3, vA2);
;                 PG8_WAIT_V(8); PG8_WAIT_L(0); PG8_BAR; PG8_MMA(1, 0, At, B0); PG8_MMA(1, 1, At, B1); PG8_BAR; PG8_SCHED;
;             }
	s_add_i32 s41, 0, 0x18000
	s_add_i32 s48, 0, 0x1c000
	v_add_u32_e32 v0, s41, v184
	v_add_u32_e32 v4, s41, v185
	v_add_u32_e32 v16, s48, v184
	v_add_u32_e32 v20, s48, v185
	ds_read_b128 v[0:3], v0
	ds_read_b128 v[4:7], v4
	ds_read_b128 v[8:11], v197
	ds_read_b128 v[12:15], v198
	ds_read_b128 v[16:19], v16
	ds_read_b128 v[20:23], v20
	ds_read_b128 v[24:27], v199
	ds_read_b128 v[28:31], v200
	s_add_u32 s50, s82, 0x80000
	s_addc_u32 s51, s83, 0
	s_mov_b32 m0, s15
	ds_read_b128 v[204:207], v194 offset:32768
	ds_read_b128 v[212:215], v194 offset:34816
	ds_read_b128 v[208:211], v195 offset:32768
	ds_read_b128 v[216:219], v195 offset:34816
	ds_read_b128 v[220:223], v194 offset:36864
	ds_read_b128 v[230:233], v194 offset:38912
	ds_read_b128 v[224:227], v195 offset:36864
	ds_read_b128 v[234:237], v195 offset:38912
	global_load_lds_dwordx4 v160, s[50:51]
	s_mov_b32 m0, s21
	s_nop 0
	global_load_lds_dwordx4 v164, s[50:51]
	s_waitcnt vmcnt(8)
	s_waitcnt lgkmcnt(0)
	s_waitcnt lgkmcnt(0)
	v_mfma_scale_f32_16x16x128_f8f6f4 v[156:159], v[0:7], v[204:211], v[156:159], v196, v196 op_sel_hi:[0,0,0]
	v_mfma_scale_f32_16x16x128_f8f6f4 v[152:155], v[8:15], v[204:211], v[152:155], v196, v196 op_sel_hi:[0,0,0]
	s_barrier
	s_setprio 3
	v_mfma_scale_f32_16x16x128_f8f6f4 v[136:139], v[8:15], v[212:219], v[136:139], v196, v196 op_sel_hi:[0,0,0]
	v_mfma_scale_f32_16x16x128_f8f6f4 v[140:143], v[0:7], v[212:219], v[140:143], v196, v196 op_sel_hi:[0,0,0]
	v_mfma_scale_f32_16x16x128_f8f6f4 v[124:127], v[0:7], v[220:227], v[124:127], v196, v196 op_sel_hi:[0,0,0]
	v_mfma_scale_f32_16x16x128_f8f6f4 v[120:123], v[8:15], v[220:227], v[120:123], v196, v196 op_sel_hi:[0,0,0]
	v_mfma_scale_f32_16x16x128_f8f6f4 v[104:107], v[8:15], v[230:237], v[104:107], v196, v196 op_sel_hi:[0,0,0]
	v_mfma_scale_f32_16x16x128_f8f6f4 v[108:111], v[0:7], v[230:237], v[108:111], v196, v196 op_sel_hi:[0,0,0]
	s_setprio 0
	s_setprio 3
	v_mfma_scale_f32_16x16x128_f8f6f4 v[148:151], v[16:23], v[204:211], v[148:151], v196, v196 op_sel_hi:[0,0,0]
	v_mfma_scale_f32_16x16x128_f8f6f4 v[144:147], v[24:31], v[204:211], v[144:147], v196, v196 op_sel_hi:[0,0,0]
	v_mfma_scale_f32_16x16x128_f8f6f4 v[128:131], v[24:31], v[212:219], v[128:131], v196, v196 op_sel_hi:[0,0,0]
	v_mfma_scale_f32_16x16x128_f8f6f4 v[132:135], v[16:23], v[212:219], v[132:135], v196, v196 op_sel_hi:[0,0,0]
	v_mfma_scale_f32_16x16x128_f8f6f4 v[116:119], v[16:23], v[220:227], v[116:119], v196, v196 op_sel_hi:[0,0,0]
	v_mfma_scale_f32_16x16x128_f8f6f4 v[112:115], v[24:31], v[220:227], v[112:115], v196, v196 op_sel_hi:[0,0,0]
	v_mfma_scale_f32_16x16x128_f8f6f4 v[96:99], v[24:31], v[230:237], v[96:99], v196, v196 op_sel_hi:[0,0,0]
	v_mfma_scale_f32_16x16x128_f8f6f4 v[100:103], v[16:23], v[230:237], v[100:103], v196, v196 op_sel_hi:[0,0,0]
	s_setprio 0
	s_barrier
	s_add_i32 s41, s41, s68
	s_mov_b32 m0, s41
	ds_read_b128 v[204:207], v194 offset:49152
	ds_read_b128 v[212:215], v194 offset:51200
	ds_read_b128 v[208:211], v195 offset:49152
	ds_read_b128 v[216:219], v195 offset:51200
	ds_read_b128 v[220:223], v194 offset:53248
	ds_read_b128 v[230:233], v194 offset:55296
	ds_read_b128 v[224:227], v195 offset:53248
	ds_read_b128 v[234:237], v195 offset:55296
	s_add_u32 s98, s58, 0x80
	s_addc_u32 s99, s59, 0
	global_load_lds_dwordx4 v162, s[98:99]
	s_add_i32 m0, s41, 0x2000
	s_add_u32 s50, s58, 0x80080
	s_addc_u32 s51, s59, 0
	s_add_i32 s41, s48, s68
	global_load_lds_dwordx4 v166, s[98:99]
	s_mov_b32 m0, s41
	s_nop 0
	global_load_lds_dwordx4 v162, s[50:51]
	s_add_i32 m0, s41, 0x2000
	s_nop 0
	global_load_lds_dwordx4 v166, s[50:51]
	s_mov_b32 m0, s35
	s_nop 0
	s_add_u32 s98, s82, 0x80
	s_addc_u32 s99, s83, 0
	global_load_lds_dwordx4 v160, s[98:99]
	s_mov_b32 m0, s53
	s_nop 0
	global_load_lds_dwordx4 v164, s[98:99]
	s_waitcnt vmcnt(8)
	s_waitcnt lgkmcnt(0)
	s_waitcnt lgkmcnt(0)
	v_mfma_scale_f32_16x16x128_f8f6f4 v[84:87], v[0:7], v[204:211], v[84:87], v196, v196 op_sel_hi:[0,0,0]
	v_mfma_scale_f32_16x16x128_f8f6f4 v[80:83], v[8:15], v[204:211], v[80:83], v196, v196 op_sel_hi:[0,0,0]
	s_barrier
	s_setprio 3
	v_mfma_scale_f32_16x16x128_f8f6f4 v[64:67], v[8:15], v[212:219], v[64:67], v196, v196 op_sel_hi:[0,0,0]
	v_mfma_scale_f32_16x16x128_f8f6f4 v[68:71], v[0:7], v[212:219], v[68:71], v196, v196 op_sel_hi:[0,0,0]
	v_mfma_scale_f32_16x16x128_f8f6f4 v[52:55], v[0:7], v[220:227], v[52:55], v196, v196 op_sel_hi:[0,0,0]
	v_mfma_scale_f32_16x16x128_f8f6f4 v[48:51], v[8:15], v[220:227], v[48:51], v196, v196 op_sel_hi:[0,0,0]
	v_mfma_scale_f32_16x16x128_f8f6f4 v[32:35], v[8:15], v[230:237], v[32:35], v196, v196 op_sel_hi:[0,0,0]
	v_mfma_scale_f32_16x16x128_f8f6f4 v[36:39], v[0:7], v[230:237], v[36:39], v196, v196 op_sel_hi:[0,0,0]
	s_setprio 0
	s_setprio 3
	v_mfma_scale_f32_16x16x128_f8f6f4 v[92:95], v[16:23], v[204:211], v[92:95], v196, v196 op_sel_hi:[0,0,0]
	v_mfma_scale_f32_16x16x128_f8f6f4 v[88:91], v[24:31], v[204:211], v[88:91], v196, v196 op_sel_hi:[0,0,0]
	v_mfma_scale_f32_16x16x128_f8f6f4 v[72:75], v[24:31], v[212:219], v[72:75], v196, v196 op_sel_hi:[0,0,0]
	v_mfma_scale_f32_16x16x128_f8f6f4 v[76:79], v[16:23], v[212:219], v[76:79], v196, v196 op_sel_hi:[0,0,0]
	v_mfma_scale_f32_16x16x128_f8f6f4 v[60:63], v[16:23], v[220:227], v[60:63], v196, v196 op_sel_hi:[0,0,0]
	v_mfma_scale_f32_16x16x128_f8f6f4 v[56:59], v[24:31], v[220:227], v[56:59], v196, v196 op_sel_hi:[0,0,0]
	v_mfma_scale_f32_16x16x128_f8f6f4 v[40:43], v[24:31], v[230:237], v[40:43], v196, v196 op_sel_hi:[0,0,0]
	v_mfma_scale_f32_16x16x128_f8f6f4 v[44:47], v[16:23], v[230:237], v[44:47], v196, v196 op_sel_hi:[0,0,0]
	s_setprio 0
	s_barrier
	s_add_i32 s40, s40, 2
	s_add_u32 s56, s56, 0x100
	s_addc_u32 s57, s57, 0
	s_add_u32 s38, s38, 0x100
	s_addc_u32 s39, s39, 0
	s_cmp_gt_u32 s40, 29
	s_cbranch_scc0 .LBB0_361
	s_and_b64 vcc, exec, s[16:17]
	s_cbranch_vccz .LBB0_364
	s_barrier

; #define PG8_STAGE(bufoff, gbase, voff) do { _Pragma("unroll") for (int _i = 0; _i < 2; ++_i) \
;         __builtin_amdgcn_global_load_lds((const unsigned*)((const char*)(gbase) + (voff)[_i]), (LAS unsigned*)(lds + (bufoff) + ldsw + _i * 8192), 16, 0, 0); } while (0)
; #define PG8_LDA(dst, b, h) do { _Pragma("unroll") for (int m = 0; m < 4; ++m) _Pragma("unroll") for (int k = 0; k < 2; ++k) dst[m][k] = *(const LAS bf16x8*)(lds + PG8_SA(b, h) + aoffk[k] + m * 2048); } while (0)
; #define PG8_LDB(dst, b, h) do { _Pragma("unroll") for (int n = 0; n < 2; ++n) _Pragma("unroll") for (int k = 0; k < 2; ++k) dst[n][k] = *(const LAS bf16x8*)(lds + PG8_SB(b, h) + boffk[k] + n * 2048); } while (0)
; #define PG8_WAIT_V(n) asm volatile("s_waitcnt vmcnt(" #n ")" ::: "memory")
; #define PG8_WAIT_L(n) asm volatile("s_waitcnt lgkmcnt(" #n ")" ::: "memory")
; #define PG8_BAR __builtin_amdgcn_s_barrier()
; #define PG8_SCHED __builtin_amdgcn_sched_barrier(0)
; template <class Epi, class Sched, class GemmT>
; __device__ __forceinline__ void gemm_phase(LAS unsigned char* lds, const GemmT& g, const Sched& S, const Epi& E, const int wid) {
;     ...
;                 PG8_LDB(B0, 0, 0); PG8_LDB(B1, 0, 1); PG8_SCHED; PG8_LDA(At, 0, 0); PG8_STAGE(PG8_SA(1, 1), a1 + hstepA, voffA);
;                 PG8_WAIT_V(8); PG8_WAIT_L(0); PG8_BAR; PG8_MMA(0, 0, At, B0); PG8_MMA(0, 1, At, B1); PG8_BAR; PG8_SCHED;
;                 PG8_LDA(At, 0, 1); PG8_STAGE(PG8_SB(0, 0), b2, vB2); PG8_STAGE(PG8_SB(0, 1), b2 + hB2, vB2); PG8_STAGE(PG8_SA(0, 0), a2, vA2);
;                 PG8_WAIT_V(8); PG8_WAIT_L(0); PG8_BAR; PG8_MMA(1, 0, At, B0); PG8_MMA(1, 1, At, B1); PG8_BAR; PG8_SCHED;
.LBB0_417:
	ds_read_b128 v[140:143], v192
	ds_read_b128 v[144:147], v193
	ds_read_b128 v[148:151], v194
	ds_read_b128 v[152:155], v195
	ds_read_b128 v[156:159], v196
	ds_read_b128 v[160:163], v197
	ds_read_b128 v[164:167], v198
	ds_read_b128 v[168:171], v199
	s_add_u32 s39, s84, 0xfff00080
	s_addc_u32 s40, s85, -1
	s_cmp_eq_u32 s38, 60
	s_cselect_b32 s87, s57, s40
	s_cselect_b32 s86, s56, s39
	s_cselect_b32 s71, s16, s37
	s_cselect_b32 s70, s5, s36
	s_add_i32 m0, s9, 0xc000
	ds_read_b128 v[172:175], v200
	ds_read_b128 v[208:211], v200 offset:2048
	ds_read_b128 v[212:215], v201
	ds_read_b128 v[216:219], v201 offset:2048
	ds_read_b128 v[220:223], v200 offset:4096
	ds_read_b128 v[224:227], v200 offset:6144
	ds_read_b128 v[230:233], v201 offset:4096
	ds_read_b128 v[234:237], v201 offset:6144
	global_load_lds_dwordx4 v128, s[84:85]
	s_add_i32 m0, s9, 0xe000
	s_nop 0
	global_load_lds_dwordx4 v132, s[84:85]
	s_waitcnt vmcnt(8)
	s_waitcnt lgkmcnt(0)
	s_waitcnt lgkmcnt(0)
	v_mfma_f32_16x16x32_bf16 v[124:127], v[140:143], v[172:175], v[124:127]
	v_mfma_f32_16x16x32_bf16 v[124:127], v[144:147], v[212:215], v[124:127]
	v_mfma_f32_16x16x32_bf16 v[120:123], v[152:155], v[212:215], v[120:123]
	v_mfma_f32_16x16x32_bf16 v[120:123], v[148:151], v[172:175], v[120:123]
	s_barrier
	s_setprio 3
	v_mfma_f32_16x16x32_bf16 v[112:115], v[148:151], v[208:211], v[112:115]
	v_mfma_f32_16x16x32_bf16 v[112:115], v[152:155], v[216:219], v[112:115]
	v_mfma_f32_16x16x32_bf16 v[116:119], v[144:147], v[216:219], v[116:119]
	v_mfma_f32_16x16x32_bf16 v[116:119], v[140:143], v[208:211], v[116:119]
	v_mfma_f32_16x16x32_bf16 v[100:103], v[140:143], v[220:223], v[100:103]
	v_mfma_f32_16x16x32_bf16 v[100:103], v[144:147], v[230:233], v[100:103]
	v_mfma_f32_16x16x32_bf16 v[96:99], v[152:155], v[230:233], v[96:99]
	v_mfma_f32_16x16x32_bf16 v[96:99], v[148:151], v[220:223], v[96:99]
	v_mfma_f32_16x16x32_bf16 v[76:79], v[148:151], v[224:227], v[76:79]
	v_mfma_f32_16x16x32_bf16 v[76:79], v[152:155], v[234:237], v[76:79]
	v_mfma_f32_16x16x32_bf16 v[84:87], v[144:147], v[234:237], v[84:87]
	v_mfma_f32_16x16x32_bf16 v[84:87], v[140:143], v[224:227], v[84:87]
	s_setprio 0
	s_setprio 3
	v_mfma_f32_16x16x32_bf16 v[108:111], v[156:159], v[172:175], v[108:111]
	v_mfma_f32_16x16x32_bf16 v[108:111], v[160:163], v[212:215], v[108:111]
	v_mfma_f32_16x16x32_bf16 v[104:107], v[168:171], v[212:215], v[104:107]
	v_mfma_f32_16x16x32_bf16 v[104:107], v[164:167], v[172:175], v[104:107]
	v_mfma_f32_16x16x32_bf16 v[88:91], v[164:167], v[208:211], v[88:91]
	v_mfma_f32_16x16x32_bf16 v[88:91], v[168:171], v[216:219], v[88:91]
	v_mfma_f32_16x16x32_bf16 v[92:95], v[160:163], v[216:219], v[92:95]
	v_mfma_f32_16x16x32_bf16 v[92:95], v[156:159], v[208:211], v[92:95]
	v_mfma_f32_16x16x32_bf16 v[68:71], v[156:159], v[220:223], v[68:71]
	v_mfma_f32_16x16x32_bf16 v[68:71], v[160:163], v[230:233], v[68:71]
	v_mfma_f32_16x16x32_bf16 v[64:67], v[168:171], v[230:233], v[64:67]
	v_mfma_f32_16x16x32_bf16 v[64:67], v[164:167], v[220:223], v[64:67]
	v_mfma_f32_16x16x32_bf16 v[40:43], v[164:167], v[224:227], v[40:43]
	v_mfma_f32_16x16x32_bf16 v[40:43], v[168:171], v[234:237], v[40:43]
	v_mfma_f32_16x16x32_bf16 v[48:51], v[160:163], v[234:237], v[48:51]
	v_mfma_f32_16x16x32_bf16 v[48:51], v[156:159], v[224:227], v[48:51]
	s_setprio 0
	s_barrier
	s_add_i32 s39, s35, s68
	s_mov_b32 m0, s39
	ds_read_b128 v[172:175], v200 offset:16384
	ds_read_b128 v[208:211], v200 offset:18432
	ds_read_b128 v[212:215], v201 offset:16384
	ds_read_b128 v[216:219], v201 offset:18432
	ds_read_b128 v[220:223], v200 offset:20480
	ds_read_b128 v[224:227], v200 offset:22528
	ds_read_b128 v[230:233], v201 offset:20480
	ds_read_b128 v[234:237], v201 offset:22528
	global_load_lds_dwordx4 v130, s[70:71]
	s_add_i32 m0, s39, 0x2000
	s_add_u32 s40, s70, 0x100000
	s_addc_u32 s41, s71, 0
	s_add_i32 s39, s69, s68
	global_load_lds_dwordx4 v134, s[70:71]
	s_mov_b32 m0, s39
	s_nop 0
	global_load_lds_dwordx4 v130, s[40:41]
	s_add_i32 m0, s39, 0x2000
	s_nop 0
	global_load_lds_dwordx4 v134, s[40:41]
	s_mov_b32 m0, s9
	s_nop 0
	global_load_lds_dwordx4 v128, s[86:87]
	s_mov_b32 m0, s29
	s_nop 0
	global_load_lds_dwordx4 v132, s[86:87]
	s_waitcnt vmcnt(8)
	s_waitcnt lgkmcnt(0)
	s_waitcnt lgkmcnt(0)
	v_mfma_f32_16x16x32_bf16 v[28:31], v[140:143], v[172:175], v[28:31]
	v_mfma_f32_16x16x32_bf16 v[28:31], v[144:147], v[212:215], v[28:31]
	v_mfma_f32_16x16x32_bf16 v[24:27], v[152:155], v[212:215], v[24:27]
	v_mfma_f32_16x16x32_bf16 v[24:27], v[148:151], v[172:175], v[24:27]
	s_barrier
	s_setprio 3
	v_mfma_f32_16x16x32_bf16 v[16:19], v[148:151], v[208:211], v[16:19]
	v_mfma_f32_16x16x32_bf16 v[16:19], v[152:155], v[216:219], v[16:19]
	v_mfma_f32_16x16x32_bf16 v[20:23], v[144:147], v[216:219], v[20:23]
	v_mfma_f32_16x16x32_bf16 v[20:23], v[140:143], v[208:211], v[20:23]
	v_mfma_f32_16x16x32_bf16 v[12:15], v[140:143], v[220:223], v[12:15]
	v_mfma_f32_16x16x32_bf16 v[12:15], v[144:147], v[230:233], v[12:15]
	v_mfma_f32_16x16x32_bf16 v[8:11], v[152:155], v[230:233], v[8:11]
	v_mfma_f32_16x16x32_bf16 v[8:11], v[148:151], v[220:223], v[8:11]
	v_mfma_f32_16x16x32_bf16 v[0:3], v[148:151], v[224:227], v[0:3]
	v_mfma_f32_16x16x32_bf16 v[0:3], v[152:155], v[234:237], v[0:3]
	v_mfma_f32_16x16x32_bf16 v[4:7], v[144:147], v[234:237], v[4:7]
	v_mfma_f32_16x16x32_bf16 v[4:7], v[140:143], v[224:227], v[4:7]
	s_setprio 0
	s_setprio 3
	v_mfma_f32_16x16x32_bf16 v[80:83], v[156:159], v[172:175], v[80:83]
	v_mfma_f32_16x16x32_bf16 v[80:83], v[160:163], v[212:215], v[80:83]
	v_mfma_f32_16x16x32_bf16 v[72:75], v[168:171], v[212:215], v[72:75]
	v_mfma_f32_16x16x32_bf16 v[72:75], v[164:167], v[172:175], v[72:75]
	v_mfma_f32_16x16x32_bf16 v[56:59], v[164:167], v[208:211], v[56:59]
	v_mfma_f32_16x16x32_bf16 v[56:59], v[168:171], v[216:219], v[56:59]
	v_mfma_f32_16x16x32_bf16 v[60:63], v[160:163], v[216:219], v[60:63]
	v_mfma_f32_16x16x32_bf16 v[60:63], v[156:159], v[208:211], v[60:63]
	v_mfma_f32_16x16x32_bf16 v[52:55], v[156:159], v[220:223], v[52:55]
	v_mfma_f32_16x16x32_bf16 v[52:55], v[160:163], v[230:233], v[52:55]
	v_mfma_f32_16x16x32_bf16 v[44:47], v[168:171], v[230:233], v[44:47]
	v_mfma_f32_16x16x32_bf16 v[44:47], v[164:167], v[220:223], v[44:47]
	v_mfma_f32_16x16x32_bf16 v[32:35], v[164:167], v[224:227], v[32:35]
	v_mfma_f32_16x16x32_bf16 v[32:35], v[168:171], v[234:237], v[32:35]
	v_mfma_f32_16x16x32_bf16 v[36:39], v[160:163], v[234:237], v[36:39]
	v_mfma_f32_16x16x32_bf16 v[36:39], v[156:159], v[224:227], v[36:39]
	s_setprio 0
	s_barrier
; #define PG8_STAGE(bufoff, gbase, voff) do { _Pragma("unroll") for (int _i = 0; _i < 2; ++_i) \
;         __builtin_amdgcn_global_load_lds((const unsigned*)((const char*)(gbase) + (voff)[_i]), (LAS unsigned*)(lds + (bufoff) + ldsw + _i * 8192), 16, 0, 0); } while (0)
; #define PG8_LDA(dst, b, h) do { _Pragma("unroll") for (int m = 0; m < 4; ++m) _Pragma("unroll") for (int k = 0; k < 2; ++k) dst[m][k] = *(const LAS bf16x8*)(lds + PG8_SA(b, h) + aoffk[k] + m * 2048); } while (0)
; #define PG8_LDB(dst, b, h) do { _Pragma("unroll") for (int n = 0; n < 2; ++n) _Pragma("unroll") for (int k = 0; k < 2; ++k) dst[n][k] = *(const LAS bf16x8*)(lds + PG8_SB(b, h) + boffk[k] + n * 2048); } while (0)
; #define PG8_WAIT_V(n) asm volatile("s_waitcnt vmcnt(" #n ")" ::: "memory")
; #define PG8_WAIT_L(n) asm volatile("s_waitcnt lgkmcnt(" #n ")" ::: "memory")
; #define PG8_BAR __builtin_amdgcn_s_barrier()
; #define PG8_SCHED __builtin_amdgcn_sched_barrier(0)
; template <class Epi, class Sched, class GemmT>
; __device__ __forceinline__ void gemm_phase(LAS unsigned char* lds, const GemmT& g, const Sched& S, const Epi& E, const int wid) {
;     ...
;                 PG8_LDB(B0, 1, 0); PG8_LDB(B1, 1, 1); PG8_SCHED; PG8_LDA(At, 1, 0); PG8_STAGE(PG8_SA(0, 1), a2 + hA2, vA2);
;                 PG8_WAIT_V(8); PG8_WAIT_L(0); PG8_BAR; PG8_MMA(0, 0, At, B0); PG8_MMA(0, 1, At, B1); PG8_BAR; PG8_SCHED;
;                 PG8_LDA(At, 1, 1); PG8_STAGE(PG8_SB(1, 0), b3, vB2); PG8_STAGE(PG8_SB(1, 1), b3 + hB2, vB2); PG8_STAGE(PG8_SA(1, 0), a3, vA2);
;                 PG8_WAIT_V(8); PG8_WAIT_L(0); PG8_BAR; PG8_MMA(1, 0, At, B0); PG8_MMA(1, 1, At, B1); PG8_BAR; PG8_SCHED;
;             }
	s_add_i32 s39, 0, 0x18000
	s_add_i32 s48, 0, 0x1c000
	v_add_u32_e32 v140, s39, v187
	v_add_u32_e32 v144, s39, v190
	v_add_u32_e32 v156, s48, v187
	v_add_u32_e32 v160, s48, v190
	ds_read_b128 v[140:143], v140
	ds_read_b128 v[144:147], v144
	ds_read_b128 v[148:151], v202
	ds_read_b128 v[152:155], v203
	ds_read_b128 v[156:159], v156
	ds_read_b128 v[160:163], v160
	ds_read_b128 v[164:167], v204
	ds_read_b128 v[168:171], v205
	s_add_u32 s40, s86, 0x100000
	s_addc_u32 s41, s87, 0
	s_mov_b32 m0, s93
	ds_read_b128 v[172:175], v200 offset:32768
	ds_read_b128 v[208:211], v200 offset:34816
	ds_read_b128 v[212:215], v201 offset:32768
	ds_read_b128 v[216:219], v201 offset:34816
	ds_read_b128 v[220:223], v200 offset:36864
	ds_read_b128 v[224:227], v200 offset:38912
	ds_read_b128 v[230:233], v201 offset:36864
	ds_read_b128 v[234:237], v201 offset:38912
	global_load_lds_dwordx4 v128, s[40:41]
	s_mov_b32 m0, s6
	s_nop 0
	global_load_lds_dwordx4 v132, s[40:41]
	s_waitcnt vmcnt(8)
	s_waitcnt lgkmcnt(0)
	s_waitcnt lgkmcnt(0)
	v_mfma_f32_16x16x32_bf16 v[124:127], v[140:143], v[172:175], v[124:127]
	v_mfma_f32_16x16x32_bf16 v[124:127], v[144:147], v[212:215], v[124:127]
	v_mfma_f32_16x16x32_bf16 v[120:123], v[152:155], v[212:215], v[120:123]
	v_mfma_f32_16x16x32_bf16 v[120:123], v[148:151], v[172:175], v[120:123]
	s_barrier
	s_setprio 3
	v_mfma_f32_16x16x32_bf16 v[112:115], v[148:151], v[208:211], v[112:115]
	v_mfma_f32_16x16x32_bf16 v[112:115], v[152:155], v[216:219], v[112:115]
	v_mfma_f32_16x16x32_bf16 v[116:119], v[144:147], v[216:219], v[116:119]
	v_mfma_f32_16x16x32_bf16 v[116:119], v[140:143], v[208:211], v[116:119]
	v_mfma_f32_16x16x32_bf16 v[100:103], v[140:143], v[220:223], v[100:103]
	v_mfma_f32_16x16x32_bf16 v[100:103], v[144:147], v[230:233], v[100:103]
	v_mfma_f32_16x16x32_bf16 v[96:99], v[152:155], v[230:233], v[96:99]
	v_mfma_f32_16x16x32_bf16 v[96:99], v[148:151], v[220:223], v[96:99]
	v_mfma_f32_16x16x32_bf16 v[76:79], v[148:151], v[224:227], v[76:79]
	v_mfma_f32_16x16x32_bf16 v[76:79], v[152:155], v[234:237], v[76:79]
	v_mfma_f32_16x16x32_bf16 v[84:87], v[144:147], v[234:237], v[84:87]
	v_mfma_f32_16x16x32_bf16 v[84:87], v[140:143], v[224:227], v[84:87]
	s_setprio 0
	s_setprio 3
	v_mfma_f32_16x16x32_bf16 v[108:111], v[156:159], v[172:175], v[108:111]
	v_mfma_f32_16x16x32_bf16 v[108:111], v[160:163], v[212:215], v[108:111]
	v_mfma_f32_16x16x32_bf16 v[104:107], v[168:171], v[212:215], v[104:107]
	v_mfma_f32_16x16x32_bf16 v[104:107], v[164:167], v[172:175], v[104:107]
	v_mfma_f32_16x16x32_bf16 v[88:91], v[164:167], v[208:211], v[88:91]
	v_mfma_f32_16x16x32_bf16 v[88:91], v[168:171], v[216:219], v[88:91]
	v_mfma_f32_16x16x32_bf16 v[92:95], v[160:163], v[216:219], v[92:95]
	v_mfma_f32_16x16x32_bf16 v[92:95], v[156:159], v[208:211], v[92:95]
	v_mfma_f32_16x16x32_bf16 v[68:71], v[156:159], v[220:223], v[68:71]
	v_mfma_f32_16x16x32_bf16 v[68:71], v[160:163], v[230:233], v[68:71]
	v_mfma_f32_16x16x32_bf16 v[64:67], v[168:171], v[230:233], v[64:67]
	v_mfma_f32_16x16x32_bf16 v[64:67], v[164:167], v[220:223], v[64:67]
	v_mfma_f32_16x16x32_bf16 v[40:43], v[164:167], v[224:227], v[40:43]
	v_mfma_f32_16x16x32_bf16 v[40:43], v[168:171], v[234:237], v[40:43]
	v_mfma_f32_16x16x32_bf16 v[48:51], v[160:163], v[234:237], v[48:51]
	v_mfma_f32_16x16x32_bf16 v[48:51], v[156:159], v[224:227], v[48:51]
	s_setprio 0
	s_barrier
	s_add_i32 s39, s39, s68
	s_mov_b32 m0, s39
	ds_read_b128 v[172:175], v200 offset:49152
	ds_read_b128 v[208:211], v200 offset:51200
	ds_read_b128 v[212:215], v201 offset:49152
	ds_read_b128 v[216:219], v201 offset:51200
	ds_read_b128 v[220:223], v200 offset:53248
	ds_read_b128 v[224:227], v200 offset:55296
	ds_read_b128 v[230:233], v201 offset:53248
	ds_read_b128 v[234:237], v201 offset:55296
	s_add_u32 s98, s70, 0x80
	s_addc_u32 s99, s71, 0
	global_load_lds_dwordx4 v130, s[98:99]
	s_add_i32 m0, s39, 0x2000
	s_add_u32 s40, s70, 0x100080
	s_addc_u32 s41, s71, 0
	s_add_i32 s39, s48, s68
	global_load_lds_dwordx4 v134, s[98:99]
	s_mov_b32 m0, s39
	s_nop 0
	global_load_lds_dwordx4 v130, s[40:41]
	s_add_i32 m0, s39, 0x2000
	s_nop 0
	global_load_lds_dwordx4 v134, s[40:41]
	s_mov_b32 m0, s7
	s_nop 0
	s_add_u32 s98, s86, 0x80
	s_addc_u32 s99, s87, 0
	global_load_lds_dwordx4 v128, s[98:99]
	s_mov_b32 m0, s12
	s_nop 0
	global_load_lds_dwordx4 v132, s[98:99]
	s_waitcnt vmcnt(8)
	s_waitcnt lgkmcnt(0)
	s_waitcnt lgkmcnt(0)
	v_mfma_f32_16x16x32_bf16 v[28:31], v[140:143], v[172:175], v[28:31]
	v_mfma_f32_16x16x32_bf16 v[28:31], v[144:147], v[212:215], v[28:31]
	v_mfma_f32_16x16x32_bf16 v[24:27], v[152:155], v[212:215], v[24:27]
	v_mfma_f32_16x16x32_bf16 v[24:27], v[148:151], v[172:175], v[24:27]
	s_barrier
	s_setprio 3
	v_mfma_f32_16x16x32_bf16 v[16:19], v[148:151], v[208:211], v[16:19]
	v_mfma_f32_16x16x32_bf16 v[16:19], v[152:155], v[216:219], v[16:19]
	v_mfma_f32_16x16x32_bf16 v[20:23], v[144:147], v[216:219], v[20:23]
	v_mfma_f32_16x16x32_bf16 v[20:23], v[140:143], v[208:211], v[20:23]
	v_mfma_f32_16x16x32_bf16 v[12:15], v[140:143], v[220:223], v[12:15]
	v_mfma_f32_16x16x32_bf16 v[12:15], v[144:147], v[230:233], v[12:15]
	v_mfma_f32_16x16x32_bf16 v[8:11], v[152:155], v[230:233], v[8:11]
	v_mfma_f32_16x16x32_bf16 v[8:11], v[148:151], v[220:223], v[8:11]
	v_mfma_f32_16x16x32_bf16 v[0:3], v[148:151], v[224:227], v[0:3]
	v_mfma_f32_16x16x32_bf16 v[0:3], v[152:155], v[234:237], v[0:3]
	v_mfma_f32_16x16x32_bf16 v[4:7], v[144:147], v[234:237], v[4:7]
	v_mfma_f32_16x16x32_bf16 v[4:7], v[140:143], v[224:227], v[4:7]
	s_setprio 0
	s_setprio 3
	v_mfma_f32_16x16x32_bf16 v[80:83], v[156:159], v[172:175], v[80:83]
	v_mfma_f32_16x16x32_bf16 v[80:83], v[160:163], v[212:215], v[80:83]
	v_mfma_f32_16x16x32_bf16 v[72:75], v[168:171], v[212:215], v[72:75]
	v_mfma_f32_16x16x32_bf16 v[72:75], v[164:167], v[172:175], v[72:75]
	v_mfma_f32_16x16x32_bf16 v[56:59], v[164:167], v[208:211], v[56:59]
	v_mfma_f32_16x16x32_bf16 v[56:59], v[168:171], v[216:219], v[56:59]
	v_mfma_f32_16x16x32_bf16 v[60:63], v[160:163], v[216:219], v[60:63]
	v_mfma_f32_16x16x32_bf16 v[60:63], v[156:159], v[208:211], v[60:63]
	v_mfma_f32_16x16x32_bf16 v[52:55], v[156:159], v[220:223], v[52:55]
	v_mfma_f32_16x16x32_bf16 v[52:55], v[160:163], v[230:233], v[52:55]
	v_mfma_f32_16x16x32_bf16 v[44:47], v[168:171], v[230:233], v[44:47]
	v_mfma_f32_16x16x32_bf16 v[44:47], v[164:167], v[220:223], v[44:47]
	v_mfma_f32_16x16x32_bf16 v[32:35], v[164:167], v[224:227], v[32:35]
	v_mfma_f32_16x16x32_bf16 v[32:35], v[168:171], v[234:237], v[32:35]
	v_mfma_f32_16x16x32_bf16 v[36:39], v[160:163], v[234:237], v[36:39]
	v_mfma_f32_16x16x32_bf16 v[36:39], v[156:159], v[224:227], v[36:39]
	s_setprio 0
	s_barrier
	s_add_i32 s38, s38, 2
	s_add_u32 s84, s84, 0x100
	s_addc_u32 s85, s85, 0
	s_add_u32 s36, s36, 0x100
	s_addc_u32 s37, s37, 0
	s_cmp_gt_u32 s38, 61
	s_cbranch_scc0 .LBB0_417
	s_and_b64 vcc, exec, s[20:21]
	s_cbranch_vccz .LBB0_420
	s_barrier

; #define PG8_STAGE(bufoff, gbase, voff) do { _Pragma("unroll") for (int _i = 0; _i < 2; ++_i) \
;         __builtin_amdgcn_global_load_lds((const unsigned*)((const char*)(gbase) + (voff)[_i]), (LAS unsigned*)(lds + (bufoff) + ldsw + _i * 8192), 16, 0, 0); } while (0)
; #define PG8_LDA(dst, b, h) do { _Pragma("unroll") for (int m = 0; m < 4; ++m) _Pragma("unroll") for (int k = 0; k < 2; ++k) dst[m][k] = *(const LAS bf16x8*)(lds + PG8_SA(b, h) + aoffk[k] + m * 2048); } while (0)
; #define PG8_LDB(dst, b, h) do { _Pragma("unroll") for (int n = 0; n < 2; ++n) _Pragma("unroll") for (int k = 0; k < 2; ++k) dst[n][k] = *(const LAS bf16x8*)(lds + PG8_SB(b, h) + boffk[k] + n * 2048); } while (0)
; #define PG8_WAIT_V(n) asm volatile("s_waitcnt vmcnt(" #n ")" ::: "memory")
; #define PG8_WAIT_L(n) asm volatile("s_waitcnt lgkmcnt(" #n ")" ::: "memory")
; #define PG8_BAR __builtin_amdgcn_s_barrier()
; #define PG8_SCHED __builtin_amdgcn_sched_barrier(0)
; template <class Epi, class Sched, class GemmT>
; __device__ __forceinline__ void gemm_phase(LAS unsigned char* lds, const GemmT& g, const Sched& S, const Epi& E, const int wid) {
;     ...
;                 PG8_LDB(B0, 0, 0); PG8_LDB(B1, 0, 1); PG8_SCHED; PG8_LDA(At, 0, 0); PG8_STAGE(PG8_SA(1, 1), a1 + hstepA, voffA);
;                 PG8_WAIT_V(8); PG8_WAIT_L(0); PG8_BAR; PG8_MMA(0, 0, At, B0); PG8_MMA(0, 1, At, B1); PG8_BAR; PG8_SCHED;
;                 PG8_LDA(At, 0, 1); PG8_STAGE(PG8_SB(0, 0), b2, vB2); PG8_STAGE(PG8_SB(0, 1), b2 + hB2, vB2); PG8_STAGE(PG8_SA(0, 0), a2, vA2);
;                 PG8_WAIT_V(8); PG8_WAIT_L(0); PG8_BAR; PG8_MMA(1, 0, At, B0); PG8_MMA(1, 1, At, B1); PG8_BAR; PG8_SCHED;
.LBB0_846:
	ds_read_b128 v[128:131], v194
	ds_read_b128 v[132:135], v195
	ds_read_b128 v[136:139], v196
	ds_read_b128 v[140:143], v197
	ds_read_b128 v[144:147], v198
	ds_read_b128 v[148:151], v199
	ds_read_b128 v[152:155], v200
	ds_read_b128 v[168:171], v201
	s_add_u32 s44, s42, 0xfff00080
	s_addc_u32 s45, s43, -1
	s_cmp_eq_u32 s62, 60
	s_cselect_b32 s51, s37, s45
	s_cselect_b32 s50, s36, s44
	s_cselect_b32 s45, s59, s61
	s_cselect_b32 s44, s41, s60
	s_add_i32 m0, s14, 0xc000
	ds_read_b128 v[172:175], v202
	ds_read_b128 v[176:179], v202 offset:2048
	ds_read_b128 v[180:183], v203
	ds_read_b128 v[184:187], v203 offset:2048
	ds_read_b128 v[208:211], v202 offset:4096
	ds_read_b128 v[212:215], v202 offset:6144
	ds_read_b128 v[216:219], v203 offset:4096
	ds_read_b128 v[220:223], v203 offset:6144
	global_load_lds_dwordx4 v156, s[42:43]
	s_add_i32 m0, s14, 0xe000
	s_nop 0
	global_load_lds_dwordx4 v160, s[42:43]
	s_waitcnt vmcnt(8)
	s_waitcnt lgkmcnt(0)
	s_waitcnt lgkmcnt(0)
	v_mfma_f32_16x16x32_bf16 v[124:127], v[128:131], v[172:175], v[124:127]
	v_mfma_f32_16x16x32_bf16 v[124:127], v[132:135], v[180:183], v[124:127]
	v_mfma_f32_16x16x32_bf16 v[120:123], v[140:143], v[180:183], v[120:123]
	v_mfma_f32_16x16x32_bf16 v[120:123], v[136:139], v[172:175], v[120:123]
	s_barrier
	s_setprio 3
	v_mfma_f32_16x16x32_bf16 v[104:107], v[136:139], v[176:179], v[104:107]
	v_mfma_f32_16x16x32_bf16 v[104:107], v[140:143], v[184:187], v[104:107]
	v_mfma_f32_16x16x32_bf16 v[108:111], v[132:135], v[184:187], v[108:111]
	v_mfma_f32_16x16x32_bf16 v[108:111], v[128:131], v[176:179], v[108:111]
	v_mfma_f32_16x16x32_bf16 v[92:95], v[128:131], v[208:211], v[92:95]
	v_mfma_f32_16x16x32_bf16 v[92:95], v[132:135], v[216:219], v[92:95]
	v_mfma_f32_16x16x32_bf16 v[88:91], v[140:143], v[216:219], v[88:91]
	v_mfma_f32_16x16x32_bf16 v[88:91], v[136:139], v[208:211], v[88:91]
	v_mfma_f32_16x16x32_bf16 v[72:75], v[136:139], v[212:215], v[72:75]
	v_mfma_f32_16x16x32_bf16 v[72:75], v[140:143], v[220:223], v[72:75]
	v_mfma_f32_16x16x32_bf16 v[76:79], v[132:135], v[220:223], v[76:79]
	v_mfma_f32_16x16x32_bf16 v[76:79], v[128:131], v[212:215], v[76:79]
	s_setprio 0
	s_setprio 3
	v_mfma_f32_16x16x32_bf16 v[116:119], v[144:147], v[172:175], v[116:119]
	v_mfma_f32_16x16x32_bf16 v[116:119], v[148:151], v[180:183], v[116:119]
	v_mfma_f32_16x16x32_bf16 v[112:115], v[168:171], v[180:183], v[112:115]
	v_mfma_f32_16x16x32_bf16 v[112:115], v[152:155], v[172:175], v[112:115]
	v_mfma_f32_16x16x32_bf16 v[96:99], v[152:155], v[176:179], v[96:99]
	v_mfma_f32_16x16x32_bf16 v[96:99], v[168:171], v[184:187], v[96:99]
	v_mfma_f32_16x16x32_bf16 v[100:103], v[148:151], v[184:187], v[100:103]
	v_mfma_f32_16x16x32_bf16 v[100:103], v[144:147], v[176:179], v[100:103]
	v_mfma_f32_16x16x32_bf16 v[84:87], v[144:147], v[208:211], v[84:87]
	v_mfma_f32_16x16x32_bf16 v[84:87], v[148:151], v[216:219], v[84:87]
	v_mfma_f32_16x16x32_bf16 v[80:83], v[168:171], v[216:219], v[80:83]
	v_mfma_f32_16x16x32_bf16 v[80:83], v[152:155], v[208:211], v[80:83]
	v_mfma_f32_16x16x32_bf16 v[64:67], v[152:155], v[212:215], v[64:67]
	v_mfma_f32_16x16x32_bf16 v[64:67], v[168:171], v[220:223], v[64:67]
	v_mfma_f32_16x16x32_bf16 v[68:71], v[148:151], v[220:223], v[68:71]
	v_mfma_f32_16x16x32_bf16 v[68:71], v[144:147], v[212:215], v[68:71]
	s_setprio 0
	s_barrier
	s_add_i32 s48, s54, s68
	s_mov_b32 m0, s48
	ds_read_b128 v[172:175], v202 offset:16384
	ds_read_b128 v[176:179], v202 offset:18432
	ds_read_b128 v[180:183], v203 offset:16384
	ds_read_b128 v[184:187], v203 offset:18432
	ds_read_b128 v[208:211], v202 offset:20480
	ds_read_b128 v[212:215], v202 offset:22528
	ds_read_b128 v[216:219], v203 offset:20480
	ds_read_b128 v[220:223], v203 offset:22528
	global_load_lds_dwordx4 v158, s[44:45]
	s_add_i32 m0, s48, 0x2000
	s_add_u32 s48, s44, 0x100000
	s_addc_u32 s49, s45, 0
	s_add_i32 s63, s55, s68
	global_load_lds_dwordx4 v162, s[44:45]
	s_mov_b32 m0, s63
	s_nop 0
	global_load_lds_dwordx4 v158, s[48:49]
	s_add_i32 m0, s63, 0x2000
	s_nop 0
	global_load_lds_dwordx4 v162, s[48:49]
	s_mov_b32 m0, s14
	s_nop 0
	global_load_lds_dwordx4 v156, s[50:51]
	s_mov_b32 m0, s15
	s_nop 0
	global_load_lds_dwordx4 v160, s[50:51]
	s_waitcnt vmcnt(8)
	s_waitcnt lgkmcnt(0)
	s_waitcnt lgkmcnt(0)
	v_mfma_f32_16x16x32_bf16 v[52:55], v[128:131], v[172:175], v[52:55]
	v_mfma_f32_16x16x32_bf16 v[52:55], v[132:135], v[180:183], v[52:55]
	v_mfma_f32_16x16x32_bf16 v[48:51], v[140:143], v[180:183], v[48:51]
	v_mfma_f32_16x16x32_bf16 v[48:51], v[136:139], v[172:175], v[48:51]
	s_barrier
	s_setprio 3
	v_mfma_f32_16x16x32_bf16 v[32:35], v[136:139], v[176:179], v[32:35]
	v_mfma_f32_16x16x32_bf16 v[32:35], v[140:143], v[184:187], v[32:35]
	v_mfma_f32_16x16x32_bf16 v[36:39], v[132:135], v[184:187], v[36:39]
	v_mfma_f32_16x16x32_bf16 v[36:39], v[128:131], v[176:179], v[36:39]
	v_mfma_f32_16x16x32_bf16 v[20:23], v[128:131], v[208:211], v[20:23]
	v_mfma_f32_16x16x32_bf16 v[20:23], v[132:135], v[216:219], v[20:23]
	v_mfma_f32_16x16x32_bf16 v[16:19], v[140:143], v[216:219], v[16:19]
	v_mfma_f32_16x16x32_bf16 v[16:19], v[136:139], v[208:211], v[16:19]
	v_mfma_f32_16x16x32_bf16 v[0:3], v[136:139], v[212:215], v[0:3]
	v_mfma_f32_16x16x32_bf16 v[0:3], v[140:143], v[220:223], v[0:3]
	v_mfma_f32_16x16x32_bf16 v[4:7], v[132:135], v[220:223], v[4:7]
	v_mfma_f32_16x16x32_bf16 v[4:7], v[128:131], v[212:215], v[4:7]
	s_setprio 0
	s_setprio 3
	v_mfma_f32_16x16x32_bf16 v[60:63], v[144:147], v[172:175], v[60:63]
	v_mfma_f32_16x16x32_bf16 v[60:63], v[148:151], v[180:183], v[60:63]
	v_mfma_f32_16x16x32_bf16 v[56:59], v[168:171], v[180:183], v[56:59]
	v_mfma_f32_16x16x32_bf16 v[56:59], v[152:155], v[172:175], v[56:59]
	v_mfma_f32_16x16x32_bf16 v[40:43], v[152:155], v[176:179], v[40:43]
	v_mfma_f32_16x16x32_bf16 v[40:43], v[168:171], v[184:187], v[40:43]
	v_mfma_f32_16x16x32_bf16 v[44:47], v[148:151], v[184:187], v[44:47]
	v_mfma_f32_16x16x32_bf16 v[44:47], v[144:147], v[176:179], v[44:47]
	v_mfma_f32_16x16x32_bf16 v[28:31], v[144:147], v[208:211], v[28:31]
	v_mfma_f32_16x16x32_bf16 v[28:31], v[148:151], v[216:219], v[28:31]
	v_mfma_f32_16x16x32_bf16 v[24:27], v[168:171], v[216:219], v[24:27]
	v_mfma_f32_16x16x32_bf16 v[24:27], v[152:155], v[208:211], v[24:27]
	v_mfma_f32_16x16x32_bf16 v[8:11], v[152:155], v[212:215], v[8:11]
	v_mfma_f32_16x16x32_bf16 v[8:11], v[168:171], v[220:223], v[8:11]
	v_mfma_f32_16x16x32_bf16 v[12:15], v[148:151], v[220:223], v[12:15]
	v_mfma_f32_16x16x32_bf16 v[12:15], v[144:147], v[212:215], v[12:15]
	s_setprio 0
	s_barrier
; #define PG8_STAGE(bufoff, gbase, voff) do { _Pragma("unroll") for (int _i = 0; _i < 2; ++_i) \
;         __builtin_amdgcn_global_load_lds((const unsigned*)((const char*)(gbase) + (voff)[_i]), (LAS unsigned*)(lds + (bufoff) + ldsw + _i * 8192), 16, 0, 0); } while (0)
; #define PG8_LDA(dst, b, h) do { _Pragma("unroll") for (int m = 0; m < 4; ++m) _Pragma("unroll") for (int k = 0; k < 2; ++k) dst[m][k] = *(const LAS bf16x8*)(lds + PG8_SA(b, h) + aoffk[k] + m * 2048); } while (0)
; #define PG8_LDB(dst, b, h) do { _Pragma("unroll") for (int n = 0; n < 2; ++n) _Pragma("unroll") for (int k = 0; k < 2; ++k) dst[n][k] = *(const LAS bf16x8*)(lds + PG8_SB(b, h) + boffk[k] + n * 2048); } while (0)
; #define PG8_WAIT_V(n) asm volatile("s_waitcnt vmcnt(" #n ")" ::: "memory")
; #define PG8_WAIT_L(n) asm volatile("s_waitcnt lgkmcnt(" #n ")" ::: "memory")
; #define PG8_BAR __builtin_amdgcn_s_barrier()
; #define PG8_SCHED __builtin_amdgcn_sched_barrier(0)
; template <class Epi, class Sched, class GemmT>
; __device__ __forceinline__ void gemm_phase(LAS unsigned char* lds, const GemmT& g, const Sched& S, const Epi& E, const int wid) {
;     ...
;                 PG8_LDB(B0, 1, 0); PG8_LDB(B1, 1, 1); PG8_SCHED; PG8_LDA(At, 1, 0); PG8_STAGE(PG8_SA(0, 1), a2 + hA2, vA2);
;                 PG8_WAIT_V(8); PG8_WAIT_L(0); PG8_BAR; PG8_MMA(0, 0, At, B0); PG8_MMA(0, 1, At, B1); PG8_BAR; PG8_SCHED;
;                 PG8_LDA(At, 1, 1); PG8_STAGE(PG8_SB(1, 0), b3, vB2); PG8_STAGE(PG8_SB(1, 1), b3 + hB2, vB2); PG8_STAGE(PG8_SA(1, 0), a3, vA2);
;                 PG8_WAIT_V(8); PG8_WAIT_L(0); PG8_BAR; PG8_MMA(1, 0, At, B0); PG8_MMA(1, 1, At, B1); PG8_BAR; PG8_SCHED;
;             }
	s_add_i32 s63, 0, 0x18000
	s_add_i32 s64, 0, 0x1c000
	v_add_u32_e32 v128, s63, v191
	v_add_u32_e32 v132, s63, v192
	v_add_u32_e32 v144, s64, v191
	v_add_u32_e32 v148, s64, v192
	ds_read_b128 v[128:131], v128
	ds_read_b128 v[132:135], v132
	ds_read_b128 v[136:139], v204
	ds_read_b128 v[140:143], v205
	ds_read_b128 v[144:147], v144
	ds_read_b128 v[148:151], v148
	ds_read_b128 v[152:155], v206
	ds_read_b128 v[168:171], v207
	s_add_u32 s48, s50, 0x100000
	s_addc_u32 s49, s51, 0
	s_mov_b32 m0, s22
	ds_read_b128 v[172:175], v202 offset:32768
	ds_read_b128 v[176:179], v202 offset:34816
	ds_read_b128 v[180:183], v203 offset:32768
	ds_read_b128 v[184:187], v203 offset:34816
	ds_read_b128 v[208:211], v202 offset:36864
	ds_read_b128 v[212:215], v202 offset:38912
	ds_read_b128 v[216:219], v203 offset:36864
	ds_read_b128 v[220:223], v203 offset:38912
	global_load_lds_dwordx4 v156, s[48:49]
	s_mov_b32 m0, s23
	s_nop 0
	global_load_lds_dwordx4 v160, s[48:49]
	s_waitcnt vmcnt(8)
	s_waitcnt lgkmcnt(0)
	s_waitcnt lgkmcnt(0)
	v_mfma_f32_16x16x32_bf16 v[124:127], v[128:131], v[172:175], v[124:127]
	v_mfma_f32_16x16x32_bf16 v[124:127], v[132:135], v[180:183], v[124:127]
	v_mfma_f32_16x16x32_bf16 v[120:123], v[140:143], v[180:183], v[120:123]
	v_mfma_f32_16x16x32_bf16 v[120:123], v[136:139], v[172:175], v[120:123]
	s_barrier
	s_setprio 3
	v_mfma_f32_16x16x32_bf16 v[104:107], v[136:139], v[176:179], v[104:107]
	v_mfma_f32_16x16x32_bf16 v[104:107], v[140:143], v[184:187], v[104:107]
	v_mfma_f32_16x16x32_bf16 v[108:111], v[132:135], v[184:187], v[108:111]
	v_mfma_f32_16x16x32_bf16 v[108:111], v[128:131], v[176:179], v[108:111]
	v_mfma_f32_16x16x32_bf16 v[92:95], v[128:131], v[208:211], v[92:95]
	v_mfma_f32_16x16x32_bf16 v[92:95], v[132:135], v[216:219], v[92:95]
	v_mfma_f32_16x16x32_bf16 v[88:91], v[140:143], v[216:219], v[88:91]
	v_mfma_f32_16x16x32_bf16 v[88:91], v[136:139], v[208:211], v[88:91]
	v_mfma_f32_16x16x32_bf16 v[72:75], v[136:139], v[212:215], v[72:75]
	v_mfma_f32_16x16x32_bf16 v[72:75], v[140:143], v[220:223], v[72:75]
	v_mfma_f32_16x16x32_bf16 v[76:79], v[132:135], v[220:223], v[76:79]
	v_mfma_f32_16x16x32_bf16 v[76:79], v[128:131], v[212:215], v[76:79]
	s_setprio 0
	s_setprio 3
	v_mfma_f32_16x16x32_bf16 v[116:119], v[144:147], v[172:175], v[116:119]
	v_mfma_f32_16x16x32_bf16 v[116:119], v[148:151], v[180:183], v[116:119]
	v_mfma_f32_16x16x32_bf16 v[112:115], v[168:171], v[180:183], v[112:115]
	v_mfma_f32_16x16x32_bf16 v[112:115], v[152:155], v[172:175], v[112:115]
	v_mfma_f32_16x16x32_bf16 v[96:99], v[152:155], v[176:179], v[96:99]
	v_mfma_f32_16x16x32_bf16 v[96:99], v[168:171], v[184:187], v[96:99]
	v_mfma_f32_16x16x32_bf16 v[100:103], v[148:151], v[184:187], v[100:103]
	v_mfma_f32_16x16x32_bf16 v[100:103], v[144:147], v[176:179], v[100:103]
	v_mfma_f32_16x16x32_bf16 v[84:87], v[144:147], v[208:211], v[84:87]
	v_mfma_f32_16x16x32_bf16 v[84:87], v[148:151], v[216:219], v[84:87]
	v_mfma_f32_16x16x32_bf16 v[80:83], v[168:171], v[216:219], v[80:83]
	v_mfma_f32_16x16x32_bf16 v[80:83], v[152:155], v[208:211], v[80:83]
	v_mfma_f32_16x16x32_bf16 v[64:67], v[152:155], v[212:215], v[64:67]
	v_mfma_f32_16x16x32_bf16 v[64:67], v[168:171], v[220:223], v[64:67]
	v_mfma_f32_16x16x32_bf16 v[68:71], v[148:151], v[220:223], v[68:71]
	v_mfma_f32_16x16x32_bf16 v[68:71], v[144:147], v[212:215], v[68:71]
	s_setprio 0
	s_barrier
	s_add_i32 s48, s63, s68
	s_mov_b32 m0, s48
	ds_read_b128 v[172:175], v202 offset:49152
	ds_read_b128 v[176:179], v202 offset:51200
	ds_read_b128 v[180:183], v203 offset:49152
	ds_read_b128 v[184:187], v203 offset:51200
	ds_read_b128 v[208:211], v202 offset:53248
	ds_read_b128 v[212:215], v202 offset:55296
	ds_read_b128 v[216:219], v203 offset:53248
	ds_read_b128 v[220:223], v203 offset:55296
	s_add_u32 s98, s44, 0x80
	s_addc_u32 s99, s45, 0
	global_load_lds_dwordx4 v158, s[98:99]
	s_add_i32 m0, s48, 0x2000
	s_add_u32 s44, s44, 0x100080
	s_addc_u32 s45, s45, 0
	s_add_i32 s48, s64, s68
	global_load_lds_dwordx4 v162, s[98:99]
	s_mov_b32 m0, s48
	s_nop 0
	global_load_lds_dwordx4 v158, s[44:45]
	s_add_i32 m0, s48, 0x2000
	s_nop 0
	global_load_lds_dwordx4 v162, s[44:45]
	s_mov_b32 m0, s34
	s_nop 0
	s_add_u32 s98, s50, 0x80
	s_addc_u32 s99, s51, 0
	global_load_lds_dwordx4 v156, s[98:99]
	s_mov_b32 m0, s35
	s_nop 0
	global_load_lds_dwordx4 v160, s[98:99]
	s_waitcnt vmcnt(8)
	s_waitcnt lgkmcnt(0)
	s_waitcnt lgkmcnt(0)
	v_mfma_f32_16x16x32_bf16 v[52:55], v[128:131], v[172:175], v[52:55]
	v_mfma_f32_16x16x32_bf16 v[52:55], v[132:135], v[180:183], v[52:55]
	v_mfma_f32_16x16x32_bf16 v[48:51], v[140:143], v[180:183], v[48:51]
	v_mfma_f32_16x16x32_bf16 v[48:51], v[136:139], v[172:175], v[48:51]
	s_barrier
	s_setprio 3
	v_mfma_f32_16x16x32_bf16 v[32:35], v[136:139], v[176:179], v[32:35]
	v_mfma_f32_16x16x32_bf16 v[32:35], v[140:143], v[184:187], v[32:35]
	v_mfma_f32_16x16x32_bf16 v[36:39], v[132:135], v[184:187], v[36:39]
	v_mfma_f32_16x16x32_bf16 v[36:39], v[128:131], v[176:179], v[36:39]
	v_mfma_f32_16x16x32_bf16 v[20:23], v[128:131], v[208:211], v[20:23]
	v_mfma_f32_16x16x32_bf16 v[20:23], v[132:135], v[216:219], v[20:23]
	v_mfma_f32_16x16x32_bf16 v[16:19], v[140:143], v[216:219], v[16:19]
	v_mfma_f32_16x16x32_bf16 v[16:19], v[136:139], v[208:211], v[16:19]
	v_mfma_f32_16x16x32_bf16 v[0:3], v[136:139], v[212:215], v[0:3]
	v_mfma_f32_16x16x32_bf16 v[0:3], v[140:143], v[220:223], v[0:3]
	v_mfma_f32_16x16x32_bf16 v[4:7], v[132:135], v[220:223], v[4:7]
	v_mfma_f32_16x16x32_bf16 v[4:7], v[128:131], v[212:215], v[4:7]
	s_setprio 0
	s_setprio 3
	v_mfma_f32_16x16x32_bf16 v[60:63], v[144:147], v[172:175], v[60:63]
	v_mfma_f32_16x16x32_bf16 v[60:63], v[148:151], v[180:183], v[60:63]
	v_mfma_f32_16x16x32_bf16 v[56:59], v[168:171], v[180:183], v[56:59]
	v_mfma_f32_16x16x32_bf16 v[56:59], v[152:155], v[172:175], v[56:59]
	v_mfma_f32_16x16x32_bf16 v[40:43], v[152:155], v[176:179], v[40:43]
	v_mfma_f32_16x16x32_bf16 v[40:43], v[168:171], v[184:187], v[40:43]
	v_mfma_f32_16x16x32_bf16 v[44:47], v[148:151], v[184:187], v[44:47]
	v_mfma_f32_16x16x32_bf16 v[44:47], v[144:147], v[176:179], v[44:47]
	v_mfma_f32_16x16x32_bf16 v[28:31], v[144:147], v[208:211], v[28:31]
	v_mfma_f32_16x16x32_bf16 v[28:31], v[148:151], v[216:219], v[28:31]
	v_mfma_f32_16x16x32_bf16 v[24:27], v[168:171], v[216:219], v[24:27]
	v_mfma_f32_16x16x32_bf16 v[24:27], v[152:155], v[208:211], v[24:27]
	v_mfma_f32_16x16x32_bf16 v[8:11], v[152:155], v[212:215], v[8:11]
	v_mfma_f32_16x16x32_bf16 v[8:11], v[168:171], v[220:223], v[8:11]
	v_mfma_f32_16x16x32_bf16 v[12:15], v[148:151], v[220:223], v[12:15]
	v_mfma_f32_16x16x32_bf16 v[12:15], v[144:147], v[212:215], v[12:15]
	s_setprio 0
	s_barrier
	s_add_i32 s62, s62, 2
	s_add_u32 s42, s42, 0x100
	s_addc_u32 s43, s43, 0
	s_add_u32 s60, s60, 0x100
	s_addc_u32 s61, s61, 0
	s_cmp_gt_u32 s62, 61
	s_cbranch_scc0 .LBB0_846
	s_and_b64 vcc, exec, s[20:21]
	s_cbranch_vccz .LBB0_849
	s_barrier

; #define PG8_STAGE(bufoff, gbase, voff) do { _Pragma("unroll") for (int _i = 0; _i < 2; ++_i) \
;         __builtin_amdgcn_global_load_lds((const unsigned*)((const char*)(gbase) + (voff)[_i]), (LAS unsigned*)(lds + (bufoff) + ldsw + _i * 8192), 16, 0, 0); } while (0)
; #define PG8_LDA(dst, b, h) do { _Pragma("unroll") for (int m = 0; m < 4; ++m) _Pragma("unroll") for (int k = 0; k < 2; ++k) dst[m][k] = *(const LAS bf16x8*)(lds + PG8_SA(b, h) + aoffk[k] + m * 2048); } while (0)
; #define PG8_LDB(dst, b, h) do { _Pragma("unroll") for (int n = 0; n < 2; ++n) _Pragma("unroll") for (int k = 0; k < 2; ++k) dst[n][k] = *(const LAS bf16x8*)(lds + PG8_SB(b, h) + boffk[k] + n * 2048); } while (0)
; #define PG8_WAIT_V(n) asm volatile("s_waitcnt vmcnt(" #n ")" ::: "memory")
; #define PG8_WAIT_L(n) asm volatile("s_waitcnt lgkmcnt(" #n ")" ::: "memory")
; #define PG8_BAR __builtin_amdgcn_s_barrier()
; #define PG8_SCHED __builtin_amdgcn_sched_barrier(0)
; template <class Epi, class Sched, class GemmT>
; __device__ __forceinline__ void gemm_phase(LAS unsigned char* lds, const GemmT& g, const Sched& S, const Epi& E, const int wid) {
;     ...
;                 PG8_LDB(B0, 0, 0); PG8_LDB(B1, 0, 1); PG8_SCHED; PG8_LDA(At, 0, 0); PG8_STAGE(PG8_SA(1, 1), a1 + hstepA, voffA);
;                 PG8_WAIT_V(8); PG8_WAIT_L(0); PG8_BAR; PG8_MMA(0, 0, At, B0); PG8_MMA(0, 1, At, B1); PG8_BAR; PG8_SCHED;
;                 PG8_LDA(At, 0, 1); PG8_STAGE(PG8_SB(0, 0), b2, vB2); PG8_STAGE(PG8_SB(0, 1), b2 + hB2, vB2); PG8_STAGE(PG8_SA(0, 0), a2, vA2);
;                 PG8_WAIT_V(8); PG8_WAIT_L(0); PG8_BAR; PG8_MMA(1, 0, At, B0); PG8_MMA(1, 1, At, B1); PG8_BAR; PG8_SCHED;
.LBB0_936:
	ds_read_b128 v[12:15], v223
	ds_read_b128 v[132:135], v224
	ds_read_b128 v[136:139], v225
	ds_read_b128 v[140:143], v226
	ds_read_b128 v[144:147], v227
	ds_read_b128 v[148:151], v229
	ds_read_b128 v[152:155], v230
	ds_read_b128 v[156:159], v231
	s_add_u32 s66, s64, 0xfff00080
	s_addc_u32 s67, s65, -1
	s_cmp_eq_u32 s81, 60
	s_cselect_b32 s71, s57, s67
	s_cselect_b32 s70, s56, s66
	s_cselect_b32 s67, s77, s79
	s_cselect_b32 s66, s63, s78
	s_add_i32 m0, s14, 0xc000
	ds_read_b128 v[160:163], v232
	ds_read_b128 v[164:167], v232 offset:2048
	ds_read_b128 v[168:171], v233
	ds_read_b128 v[172:175], v233 offset:2048
	ds_read_b128 v[188:191], v232 offset:4096
	ds_read_b128 v[192:195], v232 offset:6144
	ds_read_b128 v[196:199], v233 offset:4096
	ds_read_b128 v[200:203], v233 offset:6144
	global_load_lds_dwordx4 v176, s[64:65]
	s_add_i32 m0, s14, 0xe000
	s_nop 0
	global_load_lds_dwordx4 v180, s[64:65]
	s_waitcnt vmcnt(8)
	s_waitcnt lgkmcnt(0)
	s_waitcnt lgkmcnt(0)
	v_mfma_f32_16x16x32_bf16 v[124:127], v[12:15], v[160:163], v[124:127]
	v_mfma_f32_16x16x32_bf16 v[124:127], v[132:135], v[168:171], v[124:127]
	v_mfma_f32_16x16x32_bf16 v[120:123], v[140:143], v[168:171], v[120:123]
	v_mfma_f32_16x16x32_bf16 v[120:123], v[136:139], v[160:163], v[120:123]
	s_barrier
	s_setprio 3
	v_mfma_f32_16x16x32_bf16 v[104:107], v[136:139], v[164:167], v[104:107]
	v_mfma_f32_16x16x32_bf16 v[104:107], v[140:143], v[172:175], v[104:107]
	v_mfma_f32_16x16x32_bf16 v[40:43], v[132:135], v[172:175], v[40:43]
	v_mfma_f32_16x16x32_bf16 v[40:43], v[12:15], v[164:167], v[40:43]
	v_mfma_f32_16x16x32_bf16 v[32:35], v[12:15], v[188:191], v[32:35]
	v_mfma_f32_16x16x32_bf16 v[32:35], v[132:135], v[196:199], v[32:35]
	v_mfma_f32_16x16x32_bf16 v[96:99], v[140:143], v[196:199], v[96:99]
	v_mfma_f32_16x16x32_bf16 v[96:99], v[136:139], v[188:191], v[96:99]
	v_mfma_f32_16x16x32_bf16 v[92:95], v[136:139], v[192:195], v[92:95]
	v_mfma_f32_16x16x32_bf16 v[92:95], v[140:143], v[200:203], v[92:95]
	v_mfma_f32_16x16x32_bf16 v[112:115], v[132:135], v[200:203], v[112:115]
	v_mfma_f32_16x16x32_bf16 v[112:115], v[12:15], v[192:195], v[112:115]
	s_setprio 0
	s_setprio 3
	v_mfma_f32_16x16x32_bf16 v[68:71], v[144:147], v[160:163], v[68:71]
	v_mfma_f32_16x16x32_bf16 v[68:71], v[148:151], v[168:171], v[68:71]
	v_mfma_f32_16x16x32_bf16 v[60:63], v[156:159], v[168:171], v[60:63]
	v_mfma_f32_16x16x32_bf16 v[60:63], v[152:155], v[160:163], v[60:63]
	v_mfma_f32_16x16x32_bf16 v[20:23], v[152:155], v[164:167], v[20:23]
	v_mfma_f32_16x16x32_bf16 v[20:23], v[156:159], v[172:175], v[20:23]
	v_mfma_f32_16x16x32_bf16 v[76:79], v[148:151], v[172:175], v[76:79]
	v_mfma_f32_16x16x32_bf16 v[76:79], v[144:147], v[164:167], v[76:79]
	v_mfma_f32_16x16x32_bf16 v[72:75], v[144:147], v[188:191], v[72:75]
	v_mfma_f32_16x16x32_bf16 v[72:75], v[148:151], v[196:199], v[72:75]
	v_mfma_f32_16x16x32_bf16 v[16:19], v[156:159], v[196:199], v[16:19]
	v_mfma_f32_16x16x32_bf16 v[16:19], v[152:155], v[188:191], v[16:19]
	v_mfma_f32_16x16x32_bf16 v[80:83], v[152:155], v[192:195], v[80:83]
	v_mfma_f32_16x16x32_bf16 v[80:83], v[156:159], v[200:203], v[80:83]
	v_mfma_f32_16x16x32_bf16 v[84:87], v[148:151], v[200:203], v[84:87]
	v_mfma_f32_16x16x32_bf16 v[84:87], v[144:147], v[192:195], v[84:87]
	s_setprio 0
	s_barrier
	s_add_i32 s80, s69, s68
	s_mov_b32 m0, s80
	ds_read_b128 v[160:163], v232 offset:16384
	ds_read_b128 v[164:167], v232 offset:18432
	ds_read_b128 v[168:171], v233 offset:16384
	ds_read_b128 v[172:175], v233 offset:18432
	ds_read_b128 v[188:191], v232 offset:20480
	ds_read_b128 v[192:195], v232 offset:22528
	ds_read_b128 v[196:199], v233 offset:20480
	ds_read_b128 v[200:203], v233 offset:22528
	global_load_lds_dwordx4 v178, s[66:67]
	s_add_i32 m0, s80, 0x2000
	s_add_u32 s82, s66, 0x100000
	s_addc_u32 s83, s67, 0
	s_add_i32 s80, s72, s68
	global_load_lds_dwordx4 v182, s[66:67]
	s_mov_b32 m0, s80
	s_nop 0
	global_load_lds_dwordx4 v178, s[82:83]
	s_add_i32 m0, s80, 0x2000
	s_nop 0
	global_load_lds_dwordx4 v182, s[82:83]
	s_mov_b32 m0, s14
	s_nop 0
	s_add_u32 s100, s70, 0x80
	s_addc_u32 s101, s71, 0
	global_load_lds_dwordx4 v176, s[70:71]
	s_mov_b32 m0, s15
	s_nop 0
	global_load_lds_dwordx4 v180, s[70:71]
	s_waitcnt vmcnt(8)
	s_waitcnt lgkmcnt(0)
	s_waitcnt lgkmcnt(0)
	v_mfma_f32_16x16x32_bf16 v[56:59], v[12:15], v[160:163], v[56:59]
	v_mfma_f32_16x16x32_bf16 v[56:59], v[132:135], v[168:171], v[56:59]
	v_mfma_f32_16x16x32_bf16 v[108:111], v[136:139], v[160:163], v[108:111]
	v_mfma_f32_16x16x32_bf16 v[108:111], v[140:143], v[168:171], v[108:111]
	s_barrier
	s_setprio 3
	v_mfma_f32_16x16x32_bf16 v[36:39], v[12:15], v[164:167], v[36:39]
	v_mfma_f32_16x16x32_bf16 v[36:39], v[132:135], v[172:175], v[36:39]
	v_mfma_f32_16x16x32_bf16 v[100:103], v[136:139], v[164:167], v[100:103]
	v_mfma_f32_16x16x32_bf16 v[100:103], v[140:143], v[172:175], v[100:103]
	v_mfma_f32_16x16x32_bf16 v[28:31], v[12:15], v[188:191], v[28:31]
	v_mfma_f32_16x16x32_bf16 v[28:31], v[132:135], v[196:199], v[28:31]
	v_mfma_f32_16x16x32_bf16 v[88:91], v[136:139], v[188:191], v[88:91]
	v_mfma_f32_16x16x32_bf16 v[88:91], v[140:143], v[196:199], v[88:91]
	v_mfma_f32_16x16x32_bf16 v[24:27], v[136:139], v[192:195], v[24:27]
	v_mfma_f32_16x16x32_bf16 v[24:27], v[140:143], v[200:203], v[24:27]
	v_mfma_f32_16x16x32_bf16 v[12:15], v[12:15], v[192:195], v[64:67]
	v_mfma_f32_16x16x32_bf16 v[12:15], v[132:135], v[200:203], v[12:15]
	s_setprio 0
	s_setprio 3
	v_mfma_f32_16x16x32_bf16 v[64:67], v[144:147], v[192:195], v[116:119]
	v_mfma_f32_16x16x32_bf16 v[116:119], v[148:151], v[200:203], v[64:67]
	v_mfma_f32_16x16x32_bf16 v[44:47], v[144:147], v[160:163], v[44:47]
	v_mfma_f32_16x16x32_bf16 v[44:47], v[148:151], v[168:171], v[44:47]
	v_mfma_f32_16x16x32_bf16 v[0:3], v[152:155], v[160:163], v[0:3]
	v_mfma_f32_16x16x32_bf16 v[0:3], v[156:159], v[168:171], v[0:3]
	v_mfma_f32_16x16x32_bf16 v[48:51], v[144:147], v[164:167], v[48:51]
	v_mfma_f32_16x16x32_bf16 v[48:51], v[148:151], v[172:175], v[48:51]
	v_mfma_f32_16x16x32_bf16 v[4:7], v[152:155], v[164:167], v[4:7]
	v_mfma_f32_16x16x32_bf16 v[4:7], v[156:159], v[172:175], v[4:7]
	v_mfma_f32_16x16x32_bf16 v[64:67], v[152:155], v[192:195], v[128:131]
	v_mfma_f32_16x16x32_bf16 v[128:131], v[156:159], v[200:203], v[64:67]
	v_mfma_f32_16x16x32_bf16 v[52:55], v[144:147], v[188:191], v[52:55]
	v_mfma_f32_16x16x32_bf16 v[52:55], v[148:151], v[196:199], v[52:55]
	v_mfma_f32_16x16x32_bf16 v[8:11], v[152:155], v[188:191], v[8:11]
	v_mfma_f32_16x16x32_bf16 v[8:11], v[156:159], v[196:199], v[8:11]
	s_setprio 0
	s_barrier
; #define PG8_STAGE(bufoff, gbase, voff) do { _Pragma("unroll") for (int _i = 0; _i < 2; ++_i) \
;         __builtin_amdgcn_global_load_lds((const unsigned*)((const char*)(gbase) + (voff)[_i]), (LAS unsigned*)(lds + (bufoff) + ldsw + _i * 8192), 16, 0, 0); } while (0)
; #define PG8_LDA(dst, b, h) do { _Pragma("unroll") for (int m = 0; m < 4; ++m) _Pragma("unroll") for (int k = 0; k < 2; ++k) dst[m][k] = *(const LAS bf16x8*)(lds + PG8_SA(b, h) + aoffk[k] + m * 2048); } while (0)
; #define PG8_LDB(dst, b, h) do { _Pragma("unroll") for (int n = 0; n < 2; ++n) _Pragma("unroll") for (int k = 0; k < 2; ++k) dst[n][k] = *(const LAS bf16x8*)(lds + PG8_SB(b, h) + boffk[k] + n * 2048); } while (0)
; #define PG8_WAIT_V(n) asm volatile("s_waitcnt vmcnt(" #n ")" ::: "memory")
; #define PG8_WAIT_L(n) asm volatile("s_waitcnt lgkmcnt(" #n ")" ::: "memory")
; #define PG8_BAR __builtin_amdgcn_s_barrier()
; #define PG8_SCHED __builtin_amdgcn_sched_barrier(0)
; template <class Epi, class Sched, class GemmT>
; __device__ __forceinline__ void gemm_phase(LAS unsigned char* lds, const GemmT& g, const Sched& S, const Epi& E, const int wid) {
;     ...
;                 PG8_LDB(B0, 1, 0); PG8_LDB(B1, 1, 1); PG8_SCHED; PG8_LDA(At, 1, 0); PG8_STAGE(PG8_SA(0, 1), a2 + hA2, vA2);
;                 PG8_WAIT_V(8); PG8_WAIT_L(0); PG8_BAR; PG8_MMA(0, 0, At, B0); PG8_MMA(0, 1, At, B1); PG8_BAR; PG8_SCHED;
;                 PG8_LDA(At, 1, 1); PG8_STAGE(PG8_SB(1, 0), b3, vB2); PG8_STAGE(PG8_SB(1, 1), b3 + hB2, vB2); PG8_STAGE(PG8_SA(1, 0), a3, vA2);
;                 PG8_WAIT_V(8); PG8_WAIT_L(0); PG8_BAR; PG8_MMA(1, 0, At, B0); PG8_MMA(1, 1, At, B1); PG8_BAR; PG8_SCHED;
;             }
	s_add_i32 s80, 0, 0x18000
	s_add_i32 s82, 0, 0x1c000
	v_add_u32_e32 v64, s80, v210
	v_add_u32_e32 v132, s80, v211
	v_add_u32_e32 v144, s82, v210
	v_add_u32_e32 v148, s82, v211
	ds_read_b128 v[64:67], v64
	ds_read_b128 v[132:135], v132
	ds_read_b128 v[136:139], v234
	ds_read_b128 v[140:143], v235
	ds_read_b128 v[144:147], v144
	ds_read_b128 v[148:151], v148
	ds_read_b128 v[152:155], v236
	ds_read_b128 v[156:159], v237
	s_add_u32 s70, s70, 0x100000
	s_addc_u32 s71, s71, 0
	s_mov_b32 m0, s23
	ds_read_b128 v[160:163], v232 offset:32768
	ds_read_b128 v[164:167], v232 offset:34816
	ds_read_b128 v[168:171], v233 offset:32768
	ds_read_b128 v[172:175], v233 offset:34816
	ds_read_b128 v[188:191], v232 offset:36864
	ds_read_b128 v[192:195], v232 offset:38912
	ds_read_b128 v[196:199], v233 offset:36864
	ds_read_b128 v[200:203], v233 offset:38912
	global_load_lds_dwordx4 v176, s[70:71]
	s_mov_b32 m0, s34
	s_nop 0
	global_load_lds_dwordx4 v180, s[70:71]
	s_waitcnt vmcnt(8)
	s_waitcnt lgkmcnt(0)
	s_waitcnt lgkmcnt(0)
	v_mfma_f32_16x16x32_bf16 v[124:127], v[64:67], v[160:163], v[124:127]
	v_mfma_f32_16x16x32_bf16 v[124:127], v[132:135], v[168:171], v[124:127]
	v_mfma_f32_16x16x32_bf16 v[120:123], v[140:143], v[168:171], v[120:123]
	v_mfma_f32_16x16x32_bf16 v[120:123], v[136:139], v[160:163], v[120:123]
	s_barrier
	s_setprio 3
	v_mfma_f32_16x16x32_bf16 v[104:107], v[136:139], v[164:167], v[104:107]
	v_mfma_f32_16x16x32_bf16 v[104:107], v[140:143], v[172:175], v[104:107]
	v_mfma_f32_16x16x32_bf16 v[40:43], v[132:135], v[172:175], v[40:43]
	v_mfma_f32_16x16x32_bf16 v[40:43], v[64:67], v[164:167], v[40:43]
	v_mfma_f32_16x16x32_bf16 v[32:35], v[64:67], v[188:191], v[32:35]
	v_mfma_f32_16x16x32_bf16 v[32:35], v[132:135], v[196:199], v[32:35]
	v_mfma_f32_16x16x32_bf16 v[96:99], v[140:143], v[196:199], v[96:99]
	v_mfma_f32_16x16x32_bf16 v[96:99], v[136:139], v[188:191], v[96:99]
	v_mfma_f32_16x16x32_bf16 v[92:95], v[136:139], v[192:195], v[92:95]
	v_mfma_f32_16x16x32_bf16 v[92:95], v[140:143], v[200:203], v[92:95]
	v_mfma_f32_16x16x32_bf16 v[112:115], v[132:135], v[200:203], v[112:115]
	v_mfma_f32_16x16x32_bf16 v[112:115], v[64:67], v[192:195], v[112:115]
	s_setprio 0
	s_setprio 3
	v_mfma_f32_16x16x32_bf16 v[68:71], v[144:147], v[160:163], v[68:71]
	v_mfma_f32_16x16x32_bf16 v[68:71], v[148:151], v[168:171], v[68:71]
	v_mfma_f32_16x16x32_bf16 v[60:63], v[156:159], v[168:171], v[60:63]
	v_mfma_f32_16x16x32_bf16 v[60:63], v[152:155], v[160:163], v[60:63]
	v_mfma_f32_16x16x32_bf16 v[20:23], v[152:155], v[164:167], v[20:23]
	v_mfma_f32_16x16x32_bf16 v[20:23], v[156:159], v[172:175], v[20:23]
	v_mfma_f32_16x16x32_bf16 v[76:79], v[148:151], v[172:175], v[76:79]
	v_mfma_f32_16x16x32_bf16 v[76:79], v[144:147], v[164:167], v[76:79]
	v_mfma_f32_16x16x32_bf16 v[72:75], v[144:147], v[188:191], v[72:75]
	v_mfma_f32_16x16x32_bf16 v[72:75], v[148:151], v[196:199], v[72:75]
	v_mfma_f32_16x16x32_bf16 v[16:19], v[156:159], v[196:199], v[16:19]
	v_mfma_f32_16x16x32_bf16 v[16:19], v[152:155], v[188:191], v[16:19]
	v_mfma_f32_16x16x32_bf16 v[80:83], v[152:155], v[192:195], v[80:83]
	v_mfma_f32_16x16x32_bf16 v[80:83], v[156:159], v[200:203], v[80:83]
	v_mfma_f32_16x16x32_bf16 v[84:87], v[148:151], v[200:203], v[84:87]
	v_mfma_f32_16x16x32_bf16 v[84:87], v[144:147], v[192:195], v[84:87]
	s_setprio 0
	s_barrier
	s_add_i32 s70, s80, s68
	s_mov_b32 m0, s70
	ds_read_b128 v[160:163], v232 offset:49152
	ds_read_b128 v[164:167], v232 offset:51200
	ds_read_b128 v[168:171], v233 offset:49152
	ds_read_b128 v[172:175], v233 offset:51200
	ds_read_b128 v[188:191], v232 offset:53248
	ds_read_b128 v[192:195], v232 offset:55296
	ds_read_b128 v[196:199], v233 offset:53248
	ds_read_b128 v[200:203], v233 offset:55296
	s_add_u32 s98, s66, 0x80
	s_addc_u32 s99, s67, 0
	global_load_lds_dwordx4 v178, s[98:99]
	s_add_i32 m0, s70, 0x2000
	s_add_u32 s66, s66, 0x100080
	s_addc_u32 s67, s67, 0
	s_add_i32 s70, s82, s68
	global_load_lds_dwordx4 v182, s[98:99]
	s_mov_b32 m0, s70
	s_nop 0
	global_load_lds_dwordx4 v178, s[66:67]
	s_add_i32 m0, s70, 0x2000
	s_nop 0
	global_load_lds_dwordx4 v182, s[66:67]
	s_mov_b32 m0, s54
	s_nop 0
	global_load_lds_dwordx4 v176, s[100:101]
	s_mov_b32 m0, s55
	s_nop 0
	global_load_lds_dwordx4 v180, s[100:101]
	s_waitcnt vmcnt(8)
	s_waitcnt lgkmcnt(0)
	s_waitcnt lgkmcnt(0)
	v_mfma_f32_16x16x32_bf16 v[12:15], v[64:67], v[192:195], v[12:15]
	v_mfma_f32_16x16x32_bf16 v[56:59], v[64:67], v[160:163], v[56:59]
	v_mfma_f32_16x16x32_bf16 v[56:59], v[132:135], v[168:171], v[56:59]
	v_mfma_f32_16x16x32_bf16 v[108:111], v[136:139], v[160:163], v[108:111]
	s_barrier
	s_setprio 3
	v_mfma_f32_16x16x32_bf16 v[108:111], v[140:143], v[168:171], v[108:111]
	v_mfma_f32_16x16x32_bf16 v[36:39], v[64:67], v[164:167], v[36:39]
	v_mfma_f32_16x16x32_bf16 v[36:39], v[132:135], v[172:175], v[36:39]
	v_mfma_f32_16x16x32_bf16 v[100:103], v[136:139], v[164:167], v[100:103]
	v_mfma_f32_16x16x32_bf16 v[100:103], v[140:143], v[172:175], v[100:103]
	v_mfma_f32_16x16x32_bf16 v[28:31], v[64:67], v[188:191], v[28:31]
	v_mfma_f32_16x16x32_bf16 v[28:31], v[132:135], v[196:199], v[28:31]
	v_mfma_f32_16x16x32_bf16 v[88:91], v[136:139], v[188:191], v[88:91]
	v_mfma_f32_16x16x32_bf16 v[88:91], v[140:143], v[196:199], v[88:91]
	v_mfma_f32_16x16x32_bf16 v[64:67], v[132:135], v[200:203], v[12:15]
	v_mfma_f32_16x16x32_bf16 v[12:15], v[136:139], v[192:195], v[24:27]
	v_mfma_f32_16x16x32_bf16 v[24:27], v[140:143], v[200:203], v[12:15]
	s_setprio 0
	s_setprio 3
	v_mfma_f32_16x16x32_bf16 v[12:15], v[144:147], v[160:163], v[44:47]
	v_mfma_f32_16x16x32_bf16 v[44:47], v[148:151], v[168:171], v[12:15]
	v_mfma_f32_16x16x32_bf16 v[0:3], v[152:155], v[160:163], v[0:3]
	v_mfma_f32_16x16x32_bf16 v[0:3], v[156:159], v[168:171], v[0:3]
	v_mfma_f32_16x16x32_bf16 v[4:7], v[152:155], v[164:167], v[4:7]
	v_mfma_f32_16x16x32_bf16 v[4:7], v[156:159], v[172:175], v[4:7]
	v_mfma_f32_16x16x32_bf16 v[12:15], v[144:147], v[164:167], v[48:51]
	v_mfma_f32_16x16x32_bf16 v[48:51], v[148:151], v[172:175], v[12:15]
	v_mfma_f32_16x16x32_bf16 v[8:11], v[152:155], v[188:191], v[8:11]
	v_mfma_f32_16x16x32_bf16 v[8:11], v[156:159], v[196:199], v[8:11]
	v_mfma_f32_16x16x32_bf16 v[12:15], v[144:147], v[188:191], v[52:55]
	v_mfma_f32_16x16x32_bf16 v[52:55], v[148:151], v[196:199], v[12:15]
	v_mfma_f32_16x16x32_bf16 v[12:15], v[144:147], v[192:195], v[116:119]
	v_mfma_f32_16x16x32_bf16 v[116:119], v[148:151], v[200:203], v[12:15]
	v_mfma_f32_16x16x32_bf16 v[12:15], v[152:155], v[192:195], v[128:131]
	v_mfma_f32_16x16x32_bf16 v[128:131], v[156:159], v[200:203], v[12:15]
	s_setprio 0
	s_barrier
	s_add_i32 s81, s81, 2
	s_add_u32 s64, s64, 0x100
	s_addc_u32 s65, s65, 0
	s_add_u32 s78, s78, 0x100
	s_addc_u32 s79, s79, 0
	s_cmp_gt_u32 s81, 61
	s_cbranch_scc0 .LBB0_936
	s_and_b64 vcc, exec, s[40:41]
	s_cbranch_vccz .LBB0_939
	s_barrier

; #define PG8_STAGE(bufoff, gbase, voff) do { _Pragma("unroll") for (int _i = 0; _i < 2; ++_i) \
;         __builtin_amdgcn_global_load_lds((const unsigned*)((const char*)(gbase) + (voff)[_i]), (LAS unsigned*)(lds + (bufoff) + ldsw + _i * 8192), 16, 0, 0); } while (0)
; #define PG8_LDA(dst, b, h) do { _Pragma("unroll") for (int m = 0; m < 4; ++m) _Pragma("unroll") for (int k = 0; k < 2; ++k) dst[m][k] = *(const LAS bf16x8*)(lds + PG8_SA(b, h) + aoffk[k] + m * 2048); } while (0)
; #define PG8_LDB(dst, b, h) do { _Pragma("unroll") for (int n = 0; n < 2; ++n) _Pragma("unroll") for (int k = 0; k < 2; ++k) dst[n][k] = *(const LAS bf16x8*)(lds + PG8_SB(b, h) + boffk[k] + n * 2048); } while (0)
; #define PG8_WAIT_V(n) asm volatile("s_waitcnt vmcnt(" #n ")" ::: "memory")
; #define PG8_WAIT_L(n) asm volatile("s_waitcnt lgkmcnt(" #n ")" ::: "memory")
; #define PG8_BAR __builtin_amdgcn_s_barrier()
; #define PG8_SCHED __builtin_amdgcn_sched_barrier(0)
; template <class Epi, class Sched, class GemmT>
; __device__ __forceinline__ void gemm_phase(LAS unsigned char* lds, const GemmT& g, const Sched& S, const Epi& E, const int wid) {
;     ...
;                 PG8_LDB(B0, 0, 0); PG8_LDB(B1, 0, 1); PG8_SCHED; PG8_LDA(At, 0, 0); PG8_STAGE(PG8_SA(1, 1), a1 + hstepA, voffA);
;                 PG8_WAIT_V(8); PG8_WAIT_L(0); PG8_BAR; PG8_MMA(0, 0, At, B0); PG8_MMA(0, 1, At, B1); PG8_BAR; PG8_SCHED;
;                 PG8_LDA(At, 0, 1); PG8_STAGE(PG8_SB(0, 0), b2, vB2); PG8_STAGE(PG8_SB(0, 1), b2 + hB2, vB2); PG8_STAGE(PG8_SA(0, 0), a2, vA2);
;                 PG8_WAIT_V(8); PG8_WAIT_L(0); PG8_BAR; PG8_MMA(1, 0, At, B0); PG8_MMA(1, 1, At, B1); PG8_BAR; PG8_SCHED;
.LBB0_1096:
	ds_read_b128 v[128:131], v188
	ds_read_b128 v[132:135], v189
	ds_read_b128 v[136:139], v190
	ds_read_b128 v[140:143], v191
	ds_read_b128 v[144:147], v192
	ds_read_b128 v[148:151], v193
	ds_read_b128 v[152:155], v194
	ds_read_b128 v[156:159], v195
	s_add_u32 s24, s22, 0xffd50080
	s_addc_u32 s25, s23, -1
	s_cmpk_eq_i32 s56, 0xa8
	s_cselect_b32 s27, s19, s25
	s_cselect_b32 s26, s18, s24
	s_cselect_b32 s25, s53, s55
	s_cselect_b32 s24, s52, s54
	s_add_i32 m0, s34, 0xc000
	ds_read_b128 v[160:163], v196
	ds_read_b128 v[164:167], v196 offset:2048
	ds_read_b128 v[180:183], v197
	ds_read_b128 v[202:205], v197 offset:2048
	ds_read_b128 v[206:209], v196 offset:4096
	ds_read_b128 v[210:213], v196 offset:6144
	ds_read_b128 v[214:217], v197 offset:4096
	ds_read_b128 v[218:221], v197 offset:6144
	global_load_lds_dwordx4 v168, s[22:23]
	s_add_i32 m0, s34, 0xe000
	s_nop 0
	global_load_lds_dwordx4 v172, s[22:23]
	s_waitcnt vmcnt(8)
	s_waitcnt lgkmcnt(0)
	s_waitcnt lgkmcnt(0)
	v_mfma_f32_16x16x32_bf16 v[124:127], v[128:131], v[160:163], v[124:127]
	v_mfma_f32_16x16x32_bf16 v[124:127], v[132:135], v[180:183], v[124:127]
	v_mfma_f32_16x16x32_bf16 v[120:123], v[140:143], v[180:183], v[120:123]
	v_mfma_f32_16x16x32_bf16 v[120:123], v[136:139], v[160:163], v[120:123]
	s_barrier
	s_setprio 3
	v_mfma_f32_16x16x32_bf16 v[104:107], v[136:139], v[164:167], v[104:107]
	v_mfma_f32_16x16x32_bf16 v[104:107], v[140:143], v[202:205], v[104:107]
	v_mfma_f32_16x16x32_bf16 v[112:115], v[132:135], v[202:205], v[112:115]
	v_mfma_f32_16x16x32_bf16 v[112:115], v[128:131], v[164:167], v[112:115]
	v_mfma_f32_16x16x32_bf16 v[96:99], v[128:131], v[206:209], v[96:99]
	v_mfma_f32_16x16x32_bf16 v[96:99], v[132:135], v[214:217], v[96:99]
	v_mfma_f32_16x16x32_bf16 v[88:91], v[140:143], v[214:217], v[88:91]
	v_mfma_f32_16x16x32_bf16 v[88:91], v[136:139], v[206:209], v[88:91]
	v_mfma_f32_16x16x32_bf16 v[72:75], v[136:139], v[210:213], v[72:75]
	v_mfma_f32_16x16x32_bf16 v[72:75], v[140:143], v[218:221], v[72:75]
	v_mfma_f32_16x16x32_bf16 v[80:83], v[132:135], v[218:221], v[80:83]
	v_mfma_f32_16x16x32_bf16 v[80:83], v[128:131], v[210:213], v[80:83]
	s_setprio 0
	s_setprio 3
	v_mfma_f32_16x16x32_bf16 v[116:119], v[144:147], v[160:163], v[116:119]
	v_mfma_f32_16x16x32_bf16 v[116:119], v[148:151], v[180:183], v[116:119]
	v_mfma_f32_16x16x32_bf16 v[108:111], v[156:159], v[180:183], v[108:111]
	v_mfma_f32_16x16x32_bf16 v[108:111], v[152:155], v[160:163], v[108:111]
	v_mfma_f32_16x16x32_bf16 v[92:95], v[152:155], v[164:167], v[92:95]
	v_mfma_f32_16x16x32_bf16 v[92:95], v[156:159], v[202:205], v[92:95]
	v_mfma_f32_16x16x32_bf16 v[100:103], v[148:151], v[202:205], v[100:103]
	v_mfma_f32_16x16x32_bf16 v[100:103], v[144:147], v[164:167], v[100:103]
	v_mfma_f32_16x16x32_bf16 v[84:87], v[144:147], v[206:209], v[84:87]
	v_mfma_f32_16x16x32_bf16 v[84:87], v[148:151], v[214:217], v[84:87]
	v_mfma_f32_16x16x32_bf16 v[76:79], v[156:159], v[214:217], v[76:79]
	v_mfma_f32_16x16x32_bf16 v[76:79], v[152:155], v[206:209], v[76:79]
	v_mfma_f32_16x16x32_bf16 v[60:63], v[152:155], v[210:213], v[60:63]
	v_mfma_f32_16x16x32_bf16 v[60:63], v[156:159], v[218:221], v[60:63]
	v_mfma_f32_16x16x32_bf16 v[68:71], v[148:151], v[218:221], v[68:71]
	v_mfma_f32_16x16x32_bf16 v[68:71], v[144:147], v[210:213], v[68:71]
	s_setprio 0
	s_barrier
	s_add_i32 s57, s41, s68
	s_mov_b32 m0, s57
	ds_read_b128 v[160:163], v196 offset:16384
	ds_read_b128 v[164:167], v196 offset:18432
	ds_read_b128 v[180:183], v197 offset:16384
	ds_read_b128 v[202:205], v197 offset:18432
	ds_read_b128 v[206:209], v196 offset:20480
	ds_read_b128 v[210:213], v196 offset:22528
	ds_read_b128 v[214:217], v197 offset:20480
	ds_read_b128 v[218:221], v197 offset:22528
	global_load_lds_dwordx4 v170, s[24:25]
	s_add_i32 m0, s57, 0x2000
	s_add_u32 s58, s24, 0x2b0000
	s_addc_u32 s59, s25, 0
	s_add_i32 s57, s42, s68
	global_load_lds_dwordx4 v174, s[24:25]
	s_mov_b32 m0, s57
	s_nop 0
	global_load_lds_dwordx4 v170, s[58:59]
	s_add_i32 m0, s57, 0x2000
	s_nop 0
	global_load_lds_dwordx4 v174, s[58:59]
	s_mov_b32 m0, s34
	s_nop 0
	s_add_u32 s100, s26, 0x80
	s_addc_u32 s101, s27, 0
	global_load_lds_dwordx4 v168, s[26:27]
	s_mov_b32 m0, s35
	s_nop 0
	global_load_lds_dwordx4 v172, s[26:27]
	s_waitcnt vmcnt(8)
	s_waitcnt lgkmcnt(0)
	s_waitcnt lgkmcnt(0)
	v_mfma_f32_16x16x32_bf16 v[52:55], v[128:131], v[160:163], v[52:55]
	v_mfma_f32_16x16x32_bf16 v[52:55], v[132:135], v[180:183], v[52:55]
	v_mfma_f32_16x16x32_bf16 v[48:51], v[140:143], v[180:183], v[48:51]
	v_mfma_f32_16x16x32_bf16 v[48:51], v[136:139], v[160:163], v[48:51]
	s_barrier
	s_setprio 3
	v_mfma_f32_16x16x32_bf16 v[32:35], v[136:139], v[164:167], v[32:35]
	v_mfma_f32_16x16x32_bf16 v[32:35], v[140:143], v[202:205], v[32:35]
	v_mfma_f32_16x16x32_bf16 v[36:39], v[132:135], v[202:205], v[36:39]
	v_mfma_f32_16x16x32_bf16 v[36:39], v[128:131], v[164:167], v[36:39]
	v_mfma_f32_16x16x32_bf16 v[20:23], v[128:131], v[206:209], v[20:23]
	v_mfma_f32_16x16x32_bf16 v[20:23], v[132:135], v[214:217], v[20:23]
	v_mfma_f32_16x16x32_bf16 v[8:11], v[140:143], v[214:217], v[8:11]
	v_mfma_f32_16x16x32_bf16 v[8:11], v[136:139], v[206:209], v[8:11]
	v_mfma_f32_16x16x32_bf16 v[0:3], v[136:139], v[210:213], v[0:3]
	v_mfma_f32_16x16x32_bf16 v[0:3], v[140:143], v[218:221], v[0:3]
	v_mfma_f32_16x16x32_bf16 v[4:7], v[132:135], v[218:221], v[4:7]
	v_mfma_f32_16x16x32_bf16 v[4:7], v[128:131], v[210:213], v[4:7]
	s_setprio 0
	s_setprio 3
	v_mfma_f32_16x16x32_bf16 v[64:67], v[144:147], v[160:163], v[64:67]
	v_mfma_f32_16x16x32_bf16 v[64:67], v[148:151], v[180:183], v[64:67]
	v_mfma_f32_16x16x32_bf16 v[56:59], v[156:159], v[180:183], v[56:59]
	v_mfma_f32_16x16x32_bf16 v[56:59], v[152:155], v[160:163], v[56:59]
	v_mfma_f32_16x16x32_bf16 v[40:43], v[152:155], v[164:167], v[40:43]
	v_mfma_f32_16x16x32_bf16 v[40:43], v[156:159], v[202:205], v[40:43]
	v_mfma_f32_16x16x32_bf16 v[44:47], v[148:151], v[202:205], v[44:47]
	v_mfma_f32_16x16x32_bf16 v[44:47], v[144:147], v[164:167], v[44:47]
	v_mfma_f32_16x16x32_bf16 v[28:31], v[144:147], v[206:209], v[28:31]
	v_mfma_f32_16x16x32_bf16 v[28:31], v[148:151], v[214:217], v[28:31]
	v_mfma_f32_16x16x32_bf16 v[24:27], v[156:159], v[214:217], v[24:27]
	v_mfma_f32_16x16x32_bf16 v[24:27], v[152:155], v[206:209], v[24:27]
	v_mfma_f32_16x16x32_bf16 v[12:15], v[152:155], v[210:213], v[12:15]
	v_mfma_f32_16x16x32_bf16 v[12:15], v[156:159], v[218:221], v[12:15]
	v_mfma_f32_16x16x32_bf16 v[16:19], v[148:151], v[218:221], v[16:19]
	v_mfma_f32_16x16x32_bf16 v[16:19], v[144:147], v[210:213], v[16:19]
	s_setprio 0
	s_barrier
; #define PG8_STAGE(bufoff, gbase, voff) do { _Pragma("unroll") for (int _i = 0; _i < 2; ++_i) \
;         __builtin_amdgcn_global_load_lds((const unsigned*)((const char*)(gbase) + (voff)[_i]), (LAS unsigned*)(lds + (bufoff) + ldsw + _i * 8192), 16, 0, 0); } while (0)
; #define PG8_LDA(dst, b, h) do { _Pragma("unroll") for (int m = 0; m < 4; ++m) _Pragma("unroll") for (int k = 0; k < 2; ++k) dst[m][k] = *(const LAS bf16x8*)(lds + PG8_SA(b, h) + aoffk[k] + m * 2048); } while (0)
; #define PG8_LDB(dst, b, h) do { _Pragma("unroll") for (int n = 0; n < 2; ++n) _Pragma("unroll") for (int k = 0; k < 2; ++k) dst[n][k] = *(const LAS bf16x8*)(lds + PG8_SB(b, h) + boffk[k] + n * 2048); } while (0)
; #define PG8_WAIT_V(n) asm volatile("s_waitcnt vmcnt(" #n ")" ::: "memory")
; #define PG8_WAIT_L(n) asm volatile("s_waitcnt lgkmcnt(" #n ")" ::: "memory")
; #define PG8_BAR __builtin_amdgcn_s_barrier()
; #define PG8_SCHED __builtin_amdgcn_sched_barrier(0)
; template <class Epi, class Sched, class GemmT>
; __device__ __forceinline__ void gemm_phase(LAS unsigned char* lds, const GemmT& g, const Sched& S, const Epi& E, const int wid) {
;     ...
;                 PG8_LDB(B0, 1, 0); PG8_LDB(B1, 1, 1); PG8_SCHED; PG8_LDA(At, 1, 0); PG8_STAGE(PG8_SA(0, 1), a2 + hA2, vA2);
;                 PG8_WAIT_V(8); PG8_WAIT_L(0); PG8_BAR; PG8_MMA(0, 0, At, B0); PG8_MMA(0, 1, At, B1); PG8_BAR; PG8_SCHED;
;                 PG8_LDA(At, 1, 1); PG8_STAGE(PG8_SB(1, 0), b3, vB2); PG8_STAGE(PG8_SB(1, 1), b3 + hB2, vB2); PG8_STAGE(PG8_SA(1, 0), a3, vA2);
;                 PG8_WAIT_V(8); PG8_WAIT_L(0); PG8_BAR; PG8_MMA(1, 0, At, B0); PG8_MMA(1, 1, At, B1); PG8_BAR; PG8_SCHED;
;             }
	s_add_i32 s57, 0, 0x18000
	s_add_i32 s58, 0, 0x1c000
	v_add_u32_e32 v128, s57, v185
	v_add_u32_e32 v132, s57, v186
	v_add_u32_e32 v144, s58, v185
	v_add_u32_e32 v148, s58, v186
	ds_read_b128 v[128:131], v128
	ds_read_b128 v[132:135], v132
	ds_read_b128 v[136:139], v198
	ds_read_b128 v[140:143], v199
	ds_read_b128 v[144:147], v144
	ds_read_b128 v[148:151], v148
	ds_read_b128 v[152:155], v200
	ds_read_b128 v[156:159], v201
	s_add_u32 s26, s26, 0x2b0000
	s_addc_u32 s27, s27, 0
	s_mov_b32 m0, s36
	ds_read_b128 v[160:163], v196 offset:32768
	ds_read_b128 v[164:167], v196 offset:34816
	ds_read_b128 v[180:183], v197 offset:32768
	ds_read_b128 v[202:205], v197 offset:34816
	ds_read_b128 v[206:209], v196 offset:36864
	ds_read_b128 v[210:213], v196 offset:38912
	ds_read_b128 v[214:217], v197 offset:36864
	ds_read_b128 v[218:221], v197 offset:38912
	global_load_lds_dwordx4 v168, s[26:27]
	s_mov_b32 m0, s37
	s_nop 0
	global_load_lds_dwordx4 v172, s[26:27]
	s_waitcnt vmcnt(8)
	s_waitcnt lgkmcnt(0)
	s_waitcnt lgkmcnt(0)
	v_mfma_f32_16x16x32_bf16 v[124:127], v[128:131], v[160:163], v[124:127]
	v_mfma_f32_16x16x32_bf16 v[124:127], v[132:135], v[180:183], v[124:127]
	v_mfma_f32_16x16x32_bf16 v[120:123], v[140:143], v[180:183], v[120:123]
	v_mfma_f32_16x16x32_bf16 v[120:123], v[136:139], v[160:163], v[120:123]
	s_barrier
	s_setprio 3
	v_mfma_f32_16x16x32_bf16 v[104:107], v[136:139], v[164:167], v[104:107]
	v_mfma_f32_16x16x32_bf16 v[104:107], v[140:143], v[202:205], v[104:107]
	v_mfma_f32_16x16x32_bf16 v[112:115], v[132:135], v[202:205], v[112:115]
	v_mfma_f32_16x16x32_bf16 v[112:115], v[128:131], v[164:167], v[112:115]
	v_mfma_f32_16x16x32_bf16 v[96:99], v[128:131], v[206:209], v[96:99]
	v_mfma_f32_16x16x32_bf16 v[96:99], v[132:135], v[214:217], v[96:99]
	v_mfma_f32_16x16x32_bf16 v[88:91], v[140:143], v[214:217], v[88:91]
	v_mfma_f32_16x16x32_bf16 v[88:91], v[136:139], v[206:209], v[88:91]
	v_mfma_f32_16x16x32_bf16 v[72:75], v[136:139], v[210:213], v[72:75]
	v_mfma_f32_16x16x32_bf16 v[72:75], v[140:143], v[218:221], v[72:75]
	v_mfma_f32_16x16x32_bf16 v[80:83], v[132:135], v[218:221], v[80:83]
	v_mfma_f32_16x16x32_bf16 v[80:83], v[128:131], v[210:213], v[80:83]
	s_setprio 0
	s_setprio 3
	v_mfma_f32_16x16x32_bf16 v[116:119], v[144:147], v[160:163], v[116:119]
	v_mfma_f32_16x16x32_bf16 v[116:119], v[148:151], v[180:183], v[116:119]
	v_mfma_f32_16x16x32_bf16 v[108:111], v[156:159], v[180:183], v[108:111]
	v_mfma_f32_16x16x32_bf16 v[108:111], v[152:155], v[160:163], v[108:111]
	v_mfma_f32_16x16x32_bf16 v[92:95], v[152:155], v[164:167], v[92:95]
	v_mfma_f32_16x16x32_bf16 v[92:95], v[156:159], v[202:205], v[92:95]
	v_mfma_f32_16x16x32_bf16 v[100:103], v[148:151], v[202:205], v[100:103]
	v_mfma_f32_16x16x32_bf16 v[100:103], v[144:147], v[164:167], v[100:103]
	v_mfma_f32_16x16x32_bf16 v[84:87], v[144:147], v[206:209], v[84:87]
	v_mfma_f32_16x16x32_bf16 v[84:87], v[148:151], v[214:217], v[84:87]
	v_mfma_f32_16x16x32_bf16 v[76:79], v[156:159], v[214:217], v[76:79]
	v_mfma_f32_16x16x32_bf16 v[76:79], v[152:155], v[206:209], v[76:79]
	v_mfma_f32_16x16x32_bf16 v[60:63], v[152:155], v[210:213], v[60:63]
	v_mfma_f32_16x16x32_bf16 v[60:63], v[156:159], v[218:221], v[60:63]
	v_mfma_f32_16x16x32_bf16 v[68:71], v[148:151], v[218:221], v[68:71]
	v_mfma_f32_16x16x32_bf16 v[68:71], v[144:147], v[210:213], v[68:71]
	s_setprio 0
	s_barrier
	s_add_i32 s26, s57, s68
	s_mov_b32 m0, s26
	ds_read_b128 v[160:163], v196 offset:49152
	ds_read_b128 v[164:167], v196 offset:51200
	ds_read_b128 v[180:183], v197 offset:49152
	ds_read_b128 v[202:205], v197 offset:51200
	ds_read_b128 v[206:209], v196 offset:53248
	ds_read_b128 v[210:213], v196 offset:55296
	ds_read_b128 v[214:217], v197 offset:53248
	ds_read_b128 v[218:221], v197 offset:55296
	s_add_u32 s98, s24, 0x80
	s_addc_u32 s99, s25, 0
	global_load_lds_dwordx4 v170, s[98:99]
	s_add_i32 m0, s26, 0x2000
	s_add_u32 s24, s24, 0x2b0080
	s_addc_u32 s25, s25, 0
	s_add_i32 s26, s58, s68
	global_load_lds_dwordx4 v174, s[98:99]
	s_mov_b32 m0, s26
	s_nop 0
	global_load_lds_dwordx4 v170, s[24:25]
	s_add_i32 m0, s26, 0x2000
	s_nop 0
	global_load_lds_dwordx4 v174, s[24:25]
	s_mov_b32 m0, s39
	s_nop 0
	global_load_lds_dwordx4 v168, s[100:101]
	s_mov_b32 m0, s40
	s_nop 0
	global_load_lds_dwordx4 v172, s[100:101]
	s_waitcnt vmcnt(8)
	s_waitcnt lgkmcnt(0)
	s_waitcnt lgkmcnt(0)
	v_mfma_f32_16x16x32_bf16 v[52:55], v[128:131], v[160:163], v[52:55]
	v_mfma_f32_16x16x32_bf16 v[52:55], v[132:135], v[180:183], v[52:55]
	v_mfma_f32_16x16x32_bf16 v[48:51], v[140:143], v[180:183], v[48:51]
	v_mfma_f32_16x16x32_bf16 v[48:51], v[136:139], v[160:163], v[48:51]
	s_barrier
	s_setprio 3
	v_mfma_f32_16x16x32_bf16 v[32:35], v[136:139], v[164:167], v[32:35]
	v_mfma_f32_16x16x32_bf16 v[32:35], v[140:143], v[202:205], v[32:35]
	v_mfma_f32_16x16x32_bf16 v[36:39], v[132:135], v[202:205], v[36:39]
	v_mfma_f32_16x16x32_bf16 v[36:39], v[128:131], v[164:167], v[36:39]
	v_mfma_f32_16x16x32_bf16 v[20:23], v[128:131], v[206:209], v[20:23]
	v_mfma_f32_16x16x32_bf16 v[20:23], v[132:135], v[214:217], v[20:23]
	v_mfma_f32_16x16x32_bf16 v[8:11], v[140:143], v[214:217], v[8:11]
	v_mfma_f32_16x16x32_bf16 v[8:11], v[136:139], v[206:209], v[8:11]
	v_mfma_f32_16x16x32_bf16 v[0:3], v[136:139], v[210:213], v[0:3]
	v_mfma_f32_16x16x32_bf16 v[0:3], v[140:143], v[218:221], v[0:3]
	v_mfma_f32_16x16x32_bf16 v[4:7], v[132:135], v[218:221], v[4:7]
	v_mfma_f32_16x16x32_bf16 v[4:7], v[128:131], v[210:213], v[4:7]
	s_setprio 0
	s_setprio 3
	v_mfma_f32_16x16x32_bf16 v[64:67], v[144:147], v[160:163], v[64:67]
	v_mfma_f32_16x16x32_bf16 v[64:67], v[148:151], v[180:183], v[64:67]
	v_mfma_f32_16x16x32_bf16 v[56:59], v[156:159], v[180:183], v[56:59]
	v_mfma_f32_16x16x32_bf16 v[56:59], v[152:155], v[160:163], v[56:59]
	v_mfma_f32_16x16x32_bf16 v[40:43], v[152:155], v[164:167], v[40:43]
	v_mfma_f32_16x16x32_bf16 v[40:43], v[156:159], v[202:205], v[40:43]
	v_mfma_f32_16x16x32_bf16 v[44:47], v[148:151], v[202:205], v[44:47]
	v_mfma_f32_16x16x32_bf16 v[44:47], v[144:147], v[164:167], v[44:47]
	v_mfma_f32_16x16x32_bf16 v[28:31], v[144:147], v[206:209], v[28:31]
	v_mfma_f32_16x16x32_bf16 v[28:31], v[148:151], v[214:217], v[28:31]
	v_mfma_f32_16x16x32_bf16 v[24:27], v[156:159], v[214:217], v[24:27]
	v_mfma_f32_16x16x32_bf16 v[24:27], v[152:155], v[206:209], v[24:27]
	v_mfma_f32_16x16x32_bf16 v[12:15], v[152:155], v[210:213], v[12:15]
	v_mfma_f32_16x16x32_bf16 v[12:15], v[156:159], v[218:221], v[12:15]
	v_mfma_f32_16x16x32_bf16 v[16:19], v[148:151], v[218:221], v[16:19]
	v_mfma_f32_16x16x32_bf16 v[16:19], v[144:147], v[210:213], v[16:19]
	s_setprio 0
	s_barrier
	s_add_i32 s56, s56, 2
	s_add_u32 s22, s22, 0x100
	s_addc_u32 s23, s23, 0
	s_add_u32 s54, s54, 0x100
	s_addc_u32 s55, s55, 0
	s_cmpk_gt_u32 s56, 0xa9
	s_cbranch_scc0 .LBB0_1096
	s_and_b64 vcc, exec, s[8:9]
	s_cbranch_vccz .LBB0_1099
	s_barrier

; __global__ void __launch_bounds__(NWAVES * 64, 2) mk_fwd(Args args) {
;     extern __shared__ __attribute__((aligned(16))) unsigned char lds_raw[];
	.amdhsa_kernel _Z6mk_fwd4Args
		.amdhsa_group_segment_fixed_size 0
		.amdhsa_private_segment_fixed_size 0
		.amdhsa_kernarg_size 480
		.amdhsa_user_sgpr_count 2
		.amdhsa_user_sgpr_dispatch_ptr 0
		.amdhsa_user_sgpr_queue_ptr 0
		.amdhsa_user_sgpr_kernarg_segment_ptr 1
		.amdhsa_user_sgpr_dispatch_id 0
		.amdhsa_user_sgpr_kernarg_preload_length 0
		.amdhsa_user_sgpr_kernarg_preload_offset 0
		.amdhsa_user_sgpr_private_segment_size 0
		.amdhsa_uses_dynamic_stack 0
		.amdhsa_enable_private_segment 0
		.amdhsa_system_sgpr_workgroup_id_x 1
		.amdhsa_system_sgpr_workgroup_id_y 0
		.amdhsa_system_sgpr_workgroup_id_z 0
		.amdhsa_system_sgpr_workgroup_info 0
		.amdhsa_system_vgpr_workitem_id 0
		.amdhsa_next_free_vgpr 256
		.amdhsa_next_free_sgpr 102
		.amdhsa_accum_offset 256
		.amdhsa_reserve_vcc 1
		.amdhsa_float_round_mode_32 0
		.amdhsa_float_round_mode_16_64 0
		.amdhsa_float_denorm_mode_32 3
		.amdhsa_float_denorm_mode_16_64 3
		.amdhsa_dx10_clamp 1
		.amdhsa_ieee_mode 1
		.amdhsa_fp16_overflow 0
		.amdhsa_tg_split 0
		.amdhsa_exception_fp_ieee_invalid_op 0
		.amdhsa_exception_fp_denorm_src 0
		.amdhsa_exception_fp_ieee_div_zero 0
		.amdhsa_exception_fp_ieee_overflow 0
		.amdhsa_exception_fp_ieee_underflow 0
		.amdhsa_exception_fp_ieee_inexact 0
		.amdhsa_exception_int_div_zero 0
	.end_amdhsa_kernel

; __global__ void __launch_bounds__(NWAVES * 64, 2) mk_fwd(Args args) {
amdhsa.kernels:
  - .agpr_count:     0
    .args:
      - .offset:         0
        .size:           224
        .value_kind:     by_value
      - .offset:         224
        .size:           4
        .value_kind:     hidden_block_count_x
      - .offset:         228
        .size:           4
        .value_kind:     hidden_block_count_y
      - .offset:         232
        .size:           4
        .value_kind:     hidden_block_count_z
      - .offset:         236
        .size:           2
        .value_kind:     hidden_group_size_x
      - .offset:         238
        .size:           2
        .value_kind:     hidden_group_size_y
      - .offset:         240
        .size:           2
        .value_kind:     hidden_group_size_z
      - .offset:         242
        .size:           2
        .value_kind:     hidden_remainder_x
      - .offset:         244
        .size:           2
        .value_kind:     hidden_remainder_y
      - .offset:         246
        .size:           2
        .value_kind:     hidden_remainder_z
      - .offset:         264
        .size:           8
        .value_kind:     hidden_global_offset_x
      - .offset:         272
        .size:           8
        .value_kind:     hidden_global_offset_y
      - .offset:         280
        .size:           8
        .value_kind:     hidden_global_offset_z
      - .offset:         288
        .size:           2
        .value_kind:     hidden_grid_dims
      - .offset:         344
        .size:           4
        .value_kind:     hidden_dynamic_lds_size
    .group_segment_fixed_size: 0
    .kernarg_segment_align: 8
    .kernarg_segment_size: 480
    .language:       OpenCL C
    .language_version:
      - 2
      - 0
    .max_flat_workgroup_size: 512
    .name:           _Z6mk_fwd4Args
    .private_segment_fixed_size: 0
    .sgpr_count:     108
    .sgpr_spill_count: 111
    .symbol:         _Z6mk_fwd4Args.kd
    .uniform_work_group_size: 1
    .uses_dynamic_stack: false
    .vgpr_count:     256
    .vgpr_spill_count: 0
    .wavefront_size: 64
